# GEMM k-loops (5 sites): two-tiles-ahead register prefetch, second staging VGPR set, counted vmcnt, unrolled x2
# speedup vs baseline: 1.0163x; 1.0163x over previous
; __device__ __forceinline__ void lds_barrier() { asm volatile("s_waitcnt lgkmcnt(0)\n\ts_barrier" ::: "memory"); }
; template <class ARowF, class KOffF>
; __device__ __forceinline__ void gemm_kloop(f32x16 (&acc)[2][2], ARowF arow, KOffF koff, const u16* __restrict__ Bt, int m0, int n0, unsigned char* smem) {
;     ...
;   const u16* pa0 = arow(m0 + lr) + lc * 8; const u16* pa1 = arow(m0 + lr + 32) + lc * 8;
;   const u16* pa2 = arow(m0 + lr + 64) + lc * 8; const u16* pa3 = arow(m0 + lr + 96) + lc * 8;
;   const u16* pb0 = Bt + (size_t)(n0 + lr) * 1024 + lc * 8;
;   u32x4 ra0, ra1, ra2, ra3, rb0, rb1, rb2, rb3;
;   {
;     const size_t ko = koff(0);
;     ra0 = *(const u32x4*)(pa0 + ko); ra1 = *(const u32x4*)(pa1 + ko); ra2 = *(const u32x4*)(pa2 + ko); ra3 = *(const u32x4*)(pa3 + ko);
;     rb0 = *(const u32x4*)(pb0); rb1 = *(const u32x4*)(pb0 + 32 * 1024); rb2 = *(const u32x4*)(pb0 + 64 * 1024); rb3 = *(const u32x4*)(pb0 + 96 * 1024);
;   }
;   u16* wA0 = sA + lr * 72 + lc * 8; u16* wB0 = sB + lr * 72 + lc * 8;
;   *(u32x4*)(wA0) = ra0; *(u32x4*)(wA0 + 32 * 72) = ra1; *(u32x4*)(wA0 + 64 * 72) = ra2; *(u32x4*)(wA0 + 96 * 72) = ra3;
;   *(u32x4*)(wB0) = rb0; *(u32x4*)(wB0 + 32 * 72) = rb1; *(u32x4*)(wB0 + 64 * 72) = rb2; *(u32x4*)(wB0 + 96 * 72) = rb3;
;   lds_barrier();
; __device__ __forceinline__ void phase1(const Params& p, unsigned char* smem) {
;     ...
;     const int m0 = mt * 128;
;     const int n0 = nt < 24 ? nt * 128 : (nt < 48 ? 4096 + (nt - 24) * 128 : 8192);
;     f32x16 acc[2][2]; zero_acc(acc);
;     gemm_kloop(acc, [&](int m) { int mm = m < NTOK ? m : NTOK - 1; return hn + (size_t)mm * DM; }, [](int k0) { return (size_t)k0; }, wtin, m0, n0, smem);
.LBB0_95:
	v_mov_b32_e32 v1, v218
	s_lshl_b32 s70, s69, 7
	s_mov_b32 s40, 0
	v_ashrrev_i32_e32 v16, 3, v1
	v_add_u32_e32 v0, s70, v16
	v_lshlrev_b32_e32 v6, 4, v1
	v_and_b32_e32 v96, 0x70, v6
	v_min_i32_e32 v6, 0x3fff, v0
	v_ashrrev_i32_e32 v7, 31, v6
	v_lshlrev_b64 v[6:7], 11, v[6:7]
	v_min_i32_e32 v8, 0x3fdf, v0
	v_lshl_add_u64 v[6:7], s[48:49], 0, v[6:7]
	v_ashrrev_i32_e32 v9, 31, v8
	v_lshl_add_u64 v[6:7], v[6:7], 0, v[96:97]
	v_lshlrev_b64 v[8:9], 11, v[8:9]
	v_min_i32_e32 v10, 0x3fbf, v0
	v_lshl_add_u64 v[8:9], s[48:49], 0, v[8:9]
	v_ashrrev_i32_e32 v11, 31, v10
	v_add_co_u32_e32 v6, vcc, s37, v6
	v_min_i32_e32 v2, 0x401f, v0
	v_lshl_add_u64 v[8:9], v[8:9], 0, v[96:97]
	v_lshlrev_b64 v[10:11], 11, v[10:11]
	v_add_u32_e32 v12, s71, v16
	v_addc_co_u32_e32 v7, vcc, 0, v7, vcc
	v_ashrrev_i32_e32 v3, 31, v2
	v_lshl_add_u64 v[10:11], s[48:49], 0, v[10:11]
	v_ashrrev_i32_e32 v13, 31, v12
	v_add_co_u32_e32 v8, vcc, s44, v8
	v_lshlrev_b64 v[2:3], 11, v[2:3]
	v_lshl_add_u64 v[10:11], v[10:11], 0, v[96:97]
	v_lshlrev_b64 v[12:13], 11, v[12:13]
	v_addc_co_u32_e32 v9, vcc, 0, v9, vcc
	v_lshl_add_u64 v[4:5], s[48:49], 0, v[2:3]
	v_lshl_add_u64 v[14:15], s[12:13], 0, v[12:13]
	global_load_dwordx4 v[64:67], v[6:7], off
	global_load_dwordx4 v[72:75], v[8:9], off
	v_add_co_u32_e32 v6, vcc, s45, v10
	v_lshl_add_u64 v[4:5], v[4:5], 0, v[96:97]
	v_lshl_add_u64 v[14:15], v[14:15], 0, v[96:97]
	v_addc_co_u32_e32 v7, vcc, 0, v11, vcc
	global_load_dwordx4 v[68:71], v[4:5], off
	global_load_dwordx4 v[76:79], v[14:15], off
	v_add_co_u32_e32 v4, vcc, s44, v14
	v_or_b32_e32 v2, v2, v96
	s_nop 0
	v_addc_co_u32_e32 v5, vcc, 0, v15, vcc
	v_add_co_u32_e32 v8, vcc, s45, v14
	v_lshl_add_u64 v[100:101], s[20:21], 0, v[2:3]
	s_nop 0
	v_addc_co_u32_e32 v9, vcc, 0, v15, vcc
	global_load_dwordx4 v[88:91], v[4:5], off
	global_load_dwordx4 v[92:95], v[8:9], off
	v_add_co_u32_e32 v4, vcc, s37, v14
	v_or_b32_e32 v12, v12, v96
	s_nop 0
	v_addc_co_u32_e32 v5, vcc, 0, v15, vcc
	global_load_dwordx4 v[80:83], v[6:7], off
	global_load_dwordx4 v[84:87], v[4:5], off
	v_and_b32_e32 v4, 31, v1
	v_lshrrev_b32_e32 v5, 1, v1
	v_and_b32_e32 v1, 0x5f, v1
	v_and_or_b32 v4, v5, s47, v4
	v_and_b32_e32 v5, 16, v5
	v_mul_u32_u24_e32 v1, 0x90, v1
	v_add3_u32 v117, 16, v1, v5
	v_ashrrev_i32_e32 v1, 31, v0
	v_mul_lo_u32 v4, v4, s46
	v_cmp_gt_i64_e32 vcc, s[28:29], v[0:1]
	v_add3_u32 v118, 16, v4, v5
	v_mul_lo_u32 v6, v16, s46
	v_cndmask_b32_e32 v5, 0, v1, vcc
	v_cndmask_b32_e32 v4, v111, v0, vcc
	v_cmp_gt_i64_e32 vcc, s[30:31], v[0:1]
	v_add3_u32 v99, 16, v6, v96
	v_lshlrev_b64 v[4:5], 11, v[4:5]
	v_cndmask_b32_e32 v3, 0, v1, vcc
	v_cndmask_b32_e32 v2, v112, v0, vcc
	v_cmp_gt_i64_e32 vcc, s[34:35], v[0:1]
	v_lshlrev_b64 v[2:3], 11, v[2:3]
	v_or_b32_e32 v4, v4, v96
	v_cndmask_b32_e32 v1, 0, v1, vcc
	v_cndmask_b32_e32 v0, v113, v0, vcc
	v_lshlrev_b64 v[0:1], 11, v[0:1]
	v_or_b32_e32 v0, v0, v96
	v_or_b32_e32 v2, v2, v96
	v_lshl_add_u64 v[106:107], s[26:27], 0, v[0:1]
	v_mov_b32_e32 v0, 0
	v_lshl_add_u64 v[102:103], s[22:23], 0, v[4:5]
	v_lshl_add_u64 v[104:105], s[24:25], 0, v[2:3]
	v_lshl_add_u64 v[108:109], s[48:49], 0, v[12:13]
	s_mov_b64 s[6:7], 0
	v_mov_b32_e32 v1, v0
	v_mov_b32_e32 v2, v0
	v_lshl_add_u64 v[226:227], v[100:101], 0, s[6:7]
	v_lshl_add_u64 v[228:229], v[102:103], 0, s[6:7]
	v_lshl_add_u64 v[230:231], v[104:105], 0, s[6:7]
	v_lshl_add_u64 v[238:239], v[106:107], 0, s[6:7]
	v_lshl_add_u64 v[248:249], v[108:109], 0, s[6:7]
	global_load_dwordx4 v[222:225], v[226:227], off
	s_nop 0
	global_load_dwordx4 v[226:229], v[228:229], off
	s_nop 0
	global_load_dwordx4 v[230:233], v[230:231], off
	s_nop 0
	global_load_dwordx4 v[234:237], v[238:239], off
	v_add_co_u32_e32 v238, vcc, 0x2010000, v248
	s_nop 1
	v_addc_co_u32_e32 v239, vcc, 0, v249, vcc
	v_add_co_u32_e32 v242, vcc, 0x2020000, v248
	s_nop 1
	v_addc_co_u32_e32 v243, vcc, 0, v249, vcc
	v_add_co_u32_e32 v250, vcc, 0x2030000, v248
	global_load_dwordx4 v[238:241], v[238:239], off offset:128
	s_nop 0
	global_load_dwordx4 v[242:245], v[242:243], off offset:128
	v_addc_co_u32_e32 v251, vcc, 0, v249, vcc
	v_add_co_u32_e32 v252, vcc, 0x2040000, v248
	s_nop 1
	v_addc_co_u32_e32 v253, vcc, 0, v249, vcc
	global_load_dwordx4 v[248:251], v[250:251], off offset:128
	s_nop 0
	global_load_dwordx4 v[252:255], v[252:253], off offset:128
	s_waitcnt vmcnt(13)
	ds_write_b128 v99, v[68:71]
	s_waitcnt vmcnt(12)
	ds_write_b128 v99, v[76:79] offset:36864
	s_waitcnt vmcnt(11)
	ds_write_b128 v99, v[88:91] offset:46080
	s_waitcnt vmcnt(10)
	ds_write_b128 v99, v[92:95] offset:50688
	ds_write_b128 v99, v[64:67] offset:4608
	ds_write_b128 v99, v[72:75] offset:9216
	s_waitcnt vmcnt(9)
	ds_write_b128 v99, v[80:83] offset:13824
	s_waitcnt vmcnt(8)
	ds_write_b128 v99, v[84:87] offset:41472
	s_waitcnt lgkmcnt(0)
	s_barrier
	v_mov_b32_e32 v3, v0
	v_mov_b32_e32 v4, v0
	v_mov_b32_e32 v5, v0
	v_mov_b32_e32 v6, v0
	v_mov_b32_e32 v7, v0
	v_mov_b32_e32 v8, v0
	v_mov_b32_e32 v9, v0
	v_mov_b32_e32 v10, v0
	v_mov_b32_e32 v11, v0
	v_mov_b32_e32 v12, v0
	v_mov_b32_e32 v13, v0
	v_mov_b32_e32 v14, v0
	v_mov_b32_e32 v15, v0
	v_mov_b32_e32 v16, v0
	v_mov_b32_e32 v17, v0
	v_mov_b32_e32 v18, v0
	v_mov_b32_e32 v19, v0
	v_mov_b32_e32 v20, v0
	v_mov_b32_e32 v21, v0
	v_mov_b32_e32 v22, v0
	v_mov_b32_e32 v23, v0
	v_mov_b32_e32 v24, v0
	v_mov_b32_e32 v25, v0
	v_mov_b32_e32 v26, v0
	v_mov_b32_e32 v27, v0
	v_mov_b32_e32 v28, v0
	v_mov_b32_e32 v29, v0
	v_mov_b32_e32 v30, v0
	v_mov_b32_e32 v31, v0
	v_mov_b32_e32 v32, v0
	v_mov_b32_e32 v33, v0
	v_mov_b32_e32 v34, v0
	v_mov_b32_e32 v35, v0
	v_mov_b32_e32 v36, v0
	v_mov_b32_e32 v37, v0
	v_mov_b32_e32 v38, v0
	v_mov_b32_e32 v39, v0
	v_mov_b32_e32 v40, v0
	v_mov_b32_e32 v41, v0
	v_mov_b32_e32 v42, v0
	v_mov_b32_e32 v43, v0
	v_mov_b32_e32 v44, v0
	v_mov_b32_e32 v45, v0
	v_mov_b32_e32 v46, v0
	v_mov_b32_e32 v47, v0
	v_mov_b32_e32 v48, v0
	v_mov_b32_e32 v49, v0
	v_mov_b32_e32 v50, v0
	v_mov_b32_e32 v51, v0
	v_mov_b32_e32 v52, v0
	v_mov_b32_e32 v53, v0
	v_mov_b32_e32 v54, v0
	v_mov_b32_e32 v55, v0
	v_mov_b32_e32 v56, v0
	v_mov_b32_e32 v57, v0
	v_mov_b32_e32 v58, v0
	v_mov_b32_e32 v59, v0
	v_mov_b32_e32 v60, v0
	v_mov_b32_e32 v61, v0
	v_mov_b32_e32 v62, v0
	v_mov_b32_e32 v63, v0
	s_branch .LBB0_97
; __device__ __forceinline__ f32x16 mfma32(bf16x8 a, bf16x8 b, f32x16 c) { return __builtin_amdgcn_mfma_f32_32x32x16_bf16(a, b, c, 0, 0, 0); }
; template <class ARowF, class KOffF>
; __device__ __forceinline__ void gemm_kloop(f32x16 (&acc)[2][2], ARowF arow, KOffF koff, const u16* __restrict__ Bt, int m0, int n0, unsigned char* smem) {
;     ...
;   for (int kt = 0; kt < 16; ++kt) {
;     const int buf = kt & 1;
;     if (kt + 1 < 16) {
;       const size_t ko = koff((kt + 1) * 64); const int kb = (kt + 1) * 64;
;       ra0 = *(const u32x4*)(pa0 + ko); ra1 = *(const u32x4*)(pa1 + ko); ra2 = *(const u32x4*)(pa2 + ko); ra3 = *(const u32x4*)(pa3 + ko);
;       rb0 = *(const u32x4*)(pb0 + kb); rb1 = *(const u32x4*)(pb0 + 32 * 1024 + kb); rb2 = *(const u32x4*)(pb0 + 64 * 1024 + kb); rb3 = *(const u32x4*)(pb0 + 96 * 1024 + kb);
;     }
;     const u16* cA = sA + buf * 128 * 72 + (wm * 64 + l31) * 72 + hf * 8;
;     const u16* cB = sB + buf * 128 * 72 + (wn * 64 + l31) * 72 + hf * 8;
; #pragma unroll
;     for (int ks = 0; ks < 4; ++ks) {
;       bf16x8 a0 = *(const bf16x8*)(cA + ks * 16);
;       bf16x8 a1 = *(const bf16x8*)(cA + 32 * 72 + ks * 16);
;       bf16x8 b0 = *(const bf16x8*)(cB + ks * 16);
;       bf16x8 b1 = *(const bf16x8*)(cB + 32 * 72 + ks * 16);
;       acc[0][0] = mfma32(a0, b0, acc[0][0]);
;       acc[0][1] = mfma32(a0, b1, acc[0][1]);
;       acc[1][0] = mfma32(a1, b0, acc[1][0]);
;       acc[1][1] = mfma32(a1, b1, acc[1][1]);
.LBB0_97:
.Lgemm_p1_loop:
	v_lshl_add_u64 v[64:65], v[100:101], 0, s[6:7]
	v_lshl_add_u64 v[66:67], v[102:103], 0, s[6:7]
	v_lshl_add_u64 v[72:73], v[104:105], 0, s[6:7]
	v_lshl_add_u64 v[76:77], v[106:107], 0, s[6:7]
	v_lshl_add_u64 v[88:89], v[108:109], 0, s[6:7]
	global_load_dwordx4 v[68:71], v[64:65], off offset:128
	s_nop 0
	global_load_dwordx4 v[64:67], v[66:67], off offset:128
	s_nop 0
	global_load_dwordx4 v[72:75], v[72:73], off offset:128
	s_nop 0
	global_load_dwordx4 v[80:83], v[76:77], off offset:128
	v_add_co_u32_e32 v76, vcc, 0x2010000, v88
	s_nop 1
	v_addc_co_u32_e32 v77, vcc, 0, v89, vcc
	v_add_co_u32_e32 v84, vcc, 0x2020000, v88
	s_nop 1
	v_addc_co_u32_e32 v85, vcc, 0, v89, vcc
	v_add_co_u32_e32 v90, vcc, 0x2030000, v88
	global_load_dwordx4 v[76:79], v[76:77], off offset:256
	s_nop 0
	global_load_dwordx4 v[84:87], v[84:85], off offset:256
	v_addc_co_u32_e32 v91, vcc, 0, v89, vcc
	v_add_co_u32_e32 v92, vcc, 0x2040000, v88
	s_nop 1
	v_addc_co_u32_e32 v93, vcc, 0, v89, vcc
	global_load_dwordx4 v[88:91], v[90:91], off offset:256
	s_nop 0
	global_load_dwordx4 v[92:95], v[92:93], off offset:256
	ds_read_b128 v[120:123], v118
	ds_read_b128 v[124:127], v117 offset:36864
	ds_read_b128 v[128:131], v118 offset:32
	ds_read_b128 v[132:135], v117 offset:36896
	ds_read_b128 v[136:139], v117 offset:41472
	ds_read_b128 v[140:143], v117 offset:41504
	s_waitcnt lgkmcnt(4)
	v_mfma_f32_32x32x16_bf16 v[48:63], v[120:123], v[124:127], v[48:63]
	s_waitcnt lgkmcnt(1)
	v_mfma_f32_32x32x16_bf16 v[32:47], v[120:123], v[136:139], v[32:47]
	ds_read_b128 v[120:123], v118 offset:4608
	ds_read_b128 v[144:147], v118 offset:4640
	s_waitcnt lgkmcnt(1)
	v_mfma_f32_32x32x16_bf16 v[16:31], v[120:123], v[124:127], v[16:31]
	v_mfma_f32_32x32x16_bf16 v[0:15], v[120:123], v[136:139], v[0:15]
	v_mfma_f32_32x32x16_bf16 v[48:63], v[128:131], v[132:135], v[48:63]
	v_mfma_f32_32x32x16_bf16 v[32:47], v[128:131], v[140:143], v[32:47]
	s_waitcnt lgkmcnt(0)
	v_mfma_f32_32x32x16_bf16 v[16:31], v[144:147], v[132:135], v[16:31]
	ds_read_b128 v[120:123], v118 offset:64
	ds_read_b128 v[124:127], v117 offset:36928
	ds_read_b128 v[128:131], v118 offset:96
	ds_read_b128 v[132:135], v117 offset:36960
	v_mfma_f32_32x32x16_bf16 v[0:15], v[144:147], v[140:143], v[0:15]
	ds_read_b128 v[136:139], v117 offset:41536
	ds_read_b128 v[140:143], v117 offset:41568
	s_waitcnt lgkmcnt(4)
	v_mfma_f32_32x32x16_bf16 v[48:63], v[120:123], v[124:127], v[48:63]
	s_waitcnt lgkmcnt(1)
	v_mfma_f32_32x32x16_bf16 v[32:47], v[120:123], v[136:139], v[32:47]
	ds_read_b128 v[120:123], v118 offset:4672
	ds_read_b128 v[144:147], v118 offset:4704
	s_waitcnt lgkmcnt(1)
	v_mfma_f32_32x32x16_bf16 v[16:31], v[120:123], v[124:127], v[16:31]
	v_mfma_f32_32x32x16_bf16 v[0:15], v[120:123], v[136:139], v[0:15]
	v_mfma_f32_32x32x16_bf16 v[48:63], v[128:131], v[132:135], v[48:63]
	v_mfma_f32_32x32x16_bf16 v[32:47], v[128:131], v[140:143], v[32:47]
	s_waitcnt lgkmcnt(0)
	v_mfma_f32_32x32x16_bf16 v[16:31], v[144:147], v[132:135], v[16:31]
	v_mfma_f32_32x32x16_bf16 v[0:15], v[144:147], v[140:143], v[0:15]
	v_add_u32_e32 v96, 18432, v99
	s_waitcnt vmcnt(15)
	ds_write_b128 v96, v[222:225]
	s_waitcnt vmcnt(14)
	ds_write_b128 v96, v[226:229] offset:4608
	s_waitcnt vmcnt(13)
	ds_write_b128 v96, v[230:233] offset:9216
	s_waitcnt vmcnt(12)
	ds_write_b128 v96, v[234:237] offset:13824
	s_waitcnt vmcnt(11)
	ds_write_b128 v96, v[238:241] offset:36864
	s_waitcnt vmcnt(10)
	ds_write_b128 v96, v[242:245] offset:41472
	s_waitcnt vmcnt(9)
	ds_write_b128 v96, v[248:251] offset:46080
	s_waitcnt vmcnt(8)
	ds_write_b128 v96, v[252:255] offset:50688
	s_waitcnt lgkmcnt(0)
	s_barrier
	v_lshl_add_u64 v[226:227], v[100:101], 0, s[6:7]
	v_lshl_add_u64 v[228:229], v[102:103], 0, s[6:7]
	v_lshl_add_u64 v[230:231], v[104:105], 0, s[6:7]
	v_lshl_add_u64 v[238:239], v[106:107], 0, s[6:7]
	v_lshl_add_u64 v[248:249], v[108:109], 0, s[6:7]
	global_load_dwordx4 v[222:225], v[226:227], off offset:256
	s_nop 0
	global_load_dwordx4 v[226:229], v[228:229], off offset:256
	s_nop 0
	global_load_dwordx4 v[230:233], v[230:231], off offset:256
	s_nop 0
	global_load_dwordx4 v[234:237], v[238:239], off offset:256
	v_add_co_u32_e32 v238, vcc, 0x2010000, v248
	s_nop 1
	v_addc_co_u32_e32 v239, vcc, 0, v249, vcc
	v_add_co_u32_e32 v242, vcc, 0x2020000, v248
	s_nop 1
	v_addc_co_u32_e32 v243, vcc, 0, v249, vcc
	v_add_co_u32_e32 v250, vcc, 0x2030000, v248
	global_load_dwordx4 v[238:241], v[238:239], off offset:384
	s_nop 0
	global_load_dwordx4 v[242:245], v[242:243], off offset:384
	v_addc_co_u32_e32 v251, vcc, 0, v249, vcc
	v_add_co_u32_e32 v252, vcc, 0x2040000, v248
	s_nop 1
	v_addc_co_u32_e32 v253, vcc, 0, v249, vcc
	global_load_dwordx4 v[248:251], v[250:251], off offset:384
	s_nop 0
	global_load_dwordx4 v[252:255], v[252:253], off offset:384
	ds_read_b128 v[120:123], v118 offset:18432
	ds_read_b128 v[124:127], v117 offset:55296
	ds_read_b128 v[128:131], v118 offset:18464
	ds_read_b128 v[132:135], v117 offset:55328
	ds_read_b128 v[136:139], v117 offset:59904
	ds_read_b128 v[140:143], v117 offset:59936
	s_waitcnt lgkmcnt(4)
	v_mfma_f32_32x32x16_bf16 v[48:63], v[120:123], v[124:127], v[48:63]
	s_waitcnt lgkmcnt(1)
	v_mfma_f32_32x32x16_bf16 v[32:47], v[120:123], v[136:139], v[32:47]
	ds_read_b128 v[120:123], v118 offset:23040
	ds_read_b128 v[144:147], v118 offset:23072
	s_waitcnt lgkmcnt(1)
	v_mfma_f32_32x32x16_bf16 v[16:31], v[120:123], v[124:127], v[16:31]
	v_mfma_f32_32x32x16_bf16 v[0:15], v[120:123], v[136:139], v[0:15]
	v_mfma_f32_32x32x16_bf16 v[48:63], v[128:131], v[132:135], v[48:63]
	v_mfma_f32_32x32x16_bf16 v[32:47], v[128:131], v[140:143], v[32:47]
	s_waitcnt lgkmcnt(0)
; __device__ __forceinline__ f32x16 mfma32(bf16x8 a, bf16x8 b, f32x16 c) { return __builtin_amdgcn_mfma_f32_32x32x16_bf16(a, b, c, 0, 0, 0); }
; __device__ __forceinline__ void lds_barrier() { asm volatile("s_waitcnt lgkmcnt(0)\n\ts_barrier" ::: "memory"); }
; template <class ARowF, class KOffF>
; __device__ __forceinline__ void gemm_kloop(f32x16 (&acc)[2][2], ARowF arow, KOffF koff, const u16* __restrict__ Bt, int m0, int n0, unsigned char* smem) {
;     ...
;   for (int kt = 0; kt < 16; ++kt) {
;     const int buf = kt & 1;
;     if (kt + 1 < 16) {
;       const size_t ko = koff((kt + 1) * 64); const int kb = (kt + 1) * 64;
;       ra0 = *(const u32x4*)(pa0 + ko); ra1 = *(const u32x4*)(pa1 + ko); ra2 = *(const u32x4*)(pa2 + ko); ra3 = *(const u32x4*)(pa3 + ko);
;       rb0 = *(const u32x4*)(pb0 + kb); rb1 = *(const u32x4*)(pb0 + 32 * 1024 + kb); rb2 = *(const u32x4*)(pb0 + 64 * 1024 + kb); rb3 = *(const u32x4*)(pb0 + 96 * 1024 + kb);
;     }
;     const u16* cA = sA + buf * 128 * 72 + (wm * 64 + l31) * 72 + hf * 8;
;     const u16* cB = sB + buf * 128 * 72 + (wn * 64 + l31) * 72 + hf * 8;
; #pragma unroll
;     for (int ks = 0; ks < 4; ++ks) {
;       bf16x8 a0 = *(const bf16x8*)(cA + ks * 16);
;       bf16x8 a1 = *(const bf16x8*)(cA + 32 * 72 + ks * 16);
;       bf16x8 b0 = *(const bf16x8*)(cB + ks * 16);
;       bf16x8 b1 = *(const bf16x8*)(cB + 32 * 72 + ks * 16);
;       acc[0][0] = mfma32(a0, b0, acc[0][0]);
;       acc[0][1] = mfma32(a0, b1, acc[0][1]);
;       acc[1][0] = mfma32(a1, b0, acc[1][0]);
;       acc[1][1] = mfma32(a1, b1, acc[1][1]);
;     }
;     if (kt + 1 < 16) {
;       u16* wA = wA0 + (buf ^ 1) * 128 * 72; u16* wB = wB0 + (buf ^ 1) * 128 * 72;
;       *(u32x4*)(wA) = ra0; *(u32x4*)(wA + 32 * 72) = ra1; *(u32x4*)(wA + 64 * 72) = ra2; *(u32x4*)(wA + 96 * 72) = ra3;
;       *(u32x4*)(wB) = rb0; *(u32x4*)(wB + 32 * 72) = rb1; *(u32x4*)(wB + 64 * 72) = rb2; *(u32x4*)(wB + 96 * 72) = rb3;
;     }
;     lds_barrier();
;   }
	v_mfma_f32_32x32x16_bf16 v[16:31], v[144:147], v[132:135], v[16:31]
	ds_read_b128 v[120:123], v118 offset:18496
	ds_read_b128 v[124:127], v117 offset:55360
	ds_read_b128 v[128:131], v118 offset:18528
	ds_read_b128 v[132:135], v117 offset:55392
	v_mfma_f32_32x32x16_bf16 v[0:15], v[144:147], v[140:143], v[0:15]
	ds_read_b128 v[136:139], v117 offset:59968
	ds_read_b128 v[140:143], v117 offset:60000
	s_waitcnt lgkmcnt(4)
	v_mfma_f32_32x32x16_bf16 v[48:63], v[120:123], v[124:127], v[48:63]
	s_waitcnt lgkmcnt(1)
	v_mfma_f32_32x32x16_bf16 v[32:47], v[120:123], v[136:139], v[32:47]
	ds_read_b128 v[120:123], v118 offset:23104
	ds_read_b128 v[144:147], v118 offset:23136
	s_waitcnt lgkmcnt(1)
	v_mfma_f32_32x32x16_bf16 v[16:31], v[120:123], v[124:127], v[16:31]
	v_mfma_f32_32x32x16_bf16 v[0:15], v[120:123], v[136:139], v[0:15]
	v_mfma_f32_32x32x16_bf16 v[48:63], v[128:131], v[132:135], v[48:63]
	v_mfma_f32_32x32x16_bf16 v[32:47], v[128:131], v[140:143], v[32:47]
	s_waitcnt lgkmcnt(0)
	v_mfma_f32_32x32x16_bf16 v[16:31], v[144:147], v[132:135], v[16:31]
	v_mfma_f32_32x32x16_bf16 v[0:15], v[144:147], v[140:143], v[0:15]
	v_mov_b32_e32 v96, v99
	s_waitcnt vmcnt(15)
	ds_write_b128 v96, v[68:71]
	s_waitcnt vmcnt(14)
	ds_write_b128 v96, v[64:67] offset:4608
	s_waitcnt vmcnt(13)
	ds_write_b128 v96, v[72:75] offset:9216
	s_waitcnt vmcnt(12)
	ds_write_b128 v96, v[80:83] offset:13824
	s_waitcnt vmcnt(11)
	ds_write_b128 v96, v[76:79] offset:36864
	s_waitcnt vmcnt(10)
	ds_write_b128 v96, v[84:87] offset:41472
	s_waitcnt vmcnt(9)
	ds_write_b128 v96, v[88:91] offset:46080
	s_waitcnt vmcnt(8)
	ds_write_b128 v96, v[92:95] offset:50688
	s_waitcnt lgkmcnt(0)
	s_barrier
	s_add_u32 s6, s6, 0x100
	s_addc_u32 s7, s7, 0
	s_cmpk_lg_i32 s6, 0x700
	s_cbranch_scc1 .Lgemm_p1_loop
	ds_read_b128 v[120:123], v118
	ds_read_b128 v[124:127], v117 offset:36864
	ds_read_b128 v[128:131], v118 offset:32
	ds_read_b128 v[132:135], v117 offset:36896
	ds_read_b128 v[136:139], v117 offset:41472
	ds_read_b128 v[140:143], v117 offset:41504
	s_waitcnt lgkmcnt(4)
	v_mfma_f32_32x32x16_bf16 v[48:63], v[120:123], v[124:127], v[48:63]
	s_waitcnt lgkmcnt(1)
	v_mfma_f32_32x32x16_bf16 v[32:47], v[120:123], v[136:139], v[32:47]
	ds_read_b128 v[120:123], v118 offset:4608
	ds_read_b128 v[144:147], v118 offset:4640
	s_waitcnt lgkmcnt(1)
	v_mfma_f32_32x32x16_bf16 v[16:31], v[120:123], v[124:127], v[16:31]
	v_mfma_f32_32x32x16_bf16 v[0:15], v[120:123], v[136:139], v[0:15]
	v_mfma_f32_32x32x16_bf16 v[48:63], v[128:131], v[132:135], v[48:63]
	v_mfma_f32_32x32x16_bf16 v[32:47], v[128:131], v[140:143], v[32:47]
	s_waitcnt lgkmcnt(0)
	v_mfma_f32_32x32x16_bf16 v[16:31], v[144:147], v[132:135], v[16:31]
	ds_read_b128 v[120:123], v118 offset:64
	ds_read_b128 v[124:127], v117 offset:36928
	ds_read_b128 v[128:131], v118 offset:96
	ds_read_b128 v[132:135], v117 offset:36960
	v_mfma_f32_32x32x16_bf16 v[0:15], v[144:147], v[140:143], v[0:15]
	ds_read_b128 v[136:139], v117 offset:41536
	ds_read_b128 v[140:143], v117 offset:41568
	s_waitcnt lgkmcnt(4)
	v_mfma_f32_32x32x16_bf16 v[48:63], v[120:123], v[124:127], v[48:63]
	s_waitcnt lgkmcnt(1)
	v_mfma_f32_32x32x16_bf16 v[32:47], v[120:123], v[136:139], v[32:47]
	ds_read_b128 v[120:123], v118 offset:4672
	ds_read_b128 v[144:147], v118 offset:4704
	s_waitcnt lgkmcnt(1)
	v_mfma_f32_32x32x16_bf16 v[16:31], v[120:123], v[124:127], v[16:31]
	v_mfma_f32_32x32x16_bf16 v[0:15], v[120:123], v[136:139], v[0:15]
	v_mfma_f32_32x32x16_bf16 v[48:63], v[128:131], v[132:135], v[48:63]
	v_mfma_f32_32x32x16_bf16 v[32:47], v[128:131], v[140:143], v[32:47]
	s_waitcnt lgkmcnt(0)
	v_mfma_f32_32x32x16_bf16 v[16:31], v[144:147], v[132:135], v[16:31]
	v_mfma_f32_32x32x16_bf16 v[0:15], v[144:147], v[140:143], v[0:15]
	v_add_u32_e32 v96, 18432, v99
	s_waitcnt vmcnt(7)
	ds_write_b128 v96, v[222:225]
	s_waitcnt vmcnt(6)
	ds_write_b128 v96, v[226:229] offset:4608
	s_waitcnt vmcnt(5)
	ds_write_b128 v96, v[230:233] offset:9216
	s_waitcnt vmcnt(4)
	ds_write_b128 v96, v[234:237] offset:13824
	s_waitcnt vmcnt(3)
	ds_write_b128 v96, v[238:241] offset:36864
	s_waitcnt vmcnt(2)
	ds_write_b128 v96, v[242:245] offset:41472
	s_waitcnt vmcnt(1)
	ds_write_b128 v96, v[248:251] offset:46080
	s_waitcnt vmcnt(0)
	ds_write_b128 v96, v[252:255] offset:50688
	s_waitcnt lgkmcnt(0)
	s_barrier
	ds_read_b128 v[120:123], v118 offset:18432
	ds_read_b128 v[124:127], v117 offset:55296
	ds_read_b128 v[128:131], v118 offset:18464
	ds_read_b128 v[132:135], v117 offset:55328
	ds_read_b128 v[136:139], v117 offset:59904
	ds_read_b128 v[140:143], v117 offset:59936
	s_waitcnt lgkmcnt(4)
	v_mfma_f32_32x32x16_bf16 v[48:63], v[120:123], v[124:127], v[48:63]
	s_waitcnt lgkmcnt(1)
	v_mfma_f32_32x32x16_bf16 v[32:47], v[120:123], v[136:139], v[32:47]
	ds_read_b128 v[120:123], v118 offset:23040
	ds_read_b128 v[144:147], v118 offset:23072
	s_waitcnt lgkmcnt(1)
	v_mfma_f32_32x32x16_bf16 v[16:31], v[120:123], v[124:127], v[16:31]
	v_mfma_f32_32x32x16_bf16 v[0:15], v[120:123], v[136:139], v[0:15]
	v_mfma_f32_32x32x16_bf16 v[48:63], v[128:131], v[132:135], v[48:63]
	v_mfma_f32_32x32x16_bf16 v[32:47], v[128:131], v[140:143], v[32:47]
	s_waitcnt lgkmcnt(0)
	v_mfma_f32_32x32x16_bf16 v[16:31], v[144:147], v[132:135], v[16:31]
	ds_read_b128 v[120:123], v118 offset:18496
	ds_read_b128 v[124:127], v117 offset:55360
	ds_read_b128 v[128:131], v118 offset:18528
	ds_read_b128 v[132:135], v117 offset:55392
	v_mfma_f32_32x32x16_bf16 v[0:15], v[144:147], v[140:143], v[0:15]
	ds_read_b128 v[136:139], v117 offset:59968
	ds_read_b128 v[140:143], v117 offset:60000
	s_waitcnt lgkmcnt(4)
	v_mfma_f32_32x32x16_bf16 v[48:63], v[120:123], v[124:127], v[48:63]
	s_waitcnt lgkmcnt(1)
	v_mfma_f32_32x32x16_bf16 v[32:47], v[120:123], v[136:139], v[32:47]
	ds_read_b128 v[120:123], v118 offset:23104
	ds_read_b128 v[144:147], v118 offset:23136
	s_waitcnt lgkmcnt(1)
	v_mfma_f32_32x32x16_bf16 v[16:31], v[120:123], v[124:127], v[16:31]
	v_mfma_f32_32x32x16_bf16 v[0:15], v[120:123], v[136:139], v[0:15]
	v_mfma_f32_32x32x16_bf16 v[48:63], v[128:131], v[132:135], v[48:63]
	v_mfma_f32_32x32x16_bf16 v[32:47], v[128:131], v[140:143], v[32:47]
	s_waitcnt lgkmcnt(0)
	v_mfma_f32_32x32x16_bf16 v[16:31], v[144:147], v[132:135], v[16:31]
	v_mfma_f32_32x32x16_bf16 v[0:15], v[144:147], v[140:143], v[0:15]
	s_waitcnt lgkmcnt(0)
	s_barrier
	s_nop 5

; __device__ __forceinline__ void lds_barrier() { asm volatile("s_waitcnt lgkmcnt(0)\n\ts_barrier" ::: "memory"); }
; template <class ARowF, class KOffF>
; __device__ __forceinline__ void gemm_kloop(f32x16 (&acc)[2][2], ARowF arow, KOffF koff, const u16* __restrict__ Bt, int m0, int n0, unsigned char* smem) {
;     ...
;   const u16* pa0 = arow(m0 + lr) + lc * 8; const u16* pa1 = arow(m0 + lr + 32) + lc * 8;
;   const u16* pa2 = arow(m0 + lr + 64) + lc * 8; const u16* pa3 = arow(m0 + lr + 96) + lc * 8;
;   const u16* pb0 = Bt + (size_t)(n0 + lr) * 1024 + lc * 8;
;   u32x4 ra0, ra1, ra2, ra3, rb0, rb1, rb2, rb3;
;   {
;     const size_t ko = koff(0);
;     ra0 = *(const u32x4*)(pa0 + ko); ra1 = *(const u32x4*)(pa1 + ko); ra2 = *(const u32x4*)(pa2 + ko); ra3 = *(const u32x4*)(pa3 + ko);
;     rb0 = *(const u32x4*)(pb0); rb1 = *(const u32x4*)(pb0 + 32 * 1024); rb2 = *(const u32x4*)(pb0 + 64 * 1024); rb3 = *(const u32x4*)(pb0 + 96 * 1024);
;   }
;   u16* wA0 = sA + lr * 72 + lc * 8; u16* wB0 = sB + lr * 72 + lc * 8;
;   *(u32x4*)(wA0) = ra0; *(u32x4*)(wA0 + 32 * 72) = ra1; *(u32x4*)(wA0 + 64 * 72) = ra2; *(u32x4*)(wA0 + 96 * 72) = ra3;
;   *(u32x4*)(wB0) = rb0; *(u32x4*)(wB0 + 32 * 72) = rb1; *(u32x4*)(wB0 + 64 * 72) = rb2; *(u32x4*)(wB0 + 96 * 72) = rb3;
;   lds_barrier();
; __device__ __forceinline__ void phase4(const Params& p, unsigned char* smem) {
;     ...
;     const int m0 = mt * 128;
;     const int n0 = nt < 8 ? 3072 + nt * 128 : (nt < 16 ? 7168 + (nt - 8) * 128 : 8208 + (nt - 16) * 128);
;     f32x16 acc[2][2]; zero_acc(acc);
;     gemm_kloop(acc, [&](int m) { return hn + (size_t)tokrow_of(m) * DM; }, [](int k0) { return (size_t)k0; }, wtin, m0, n0, smem);
.LBB0_367:
	v_mov_b32_e32 v22, v218
	s_lshl_b32 s66, s64, 7
	v_ashrrev_i32_e32 v23, 3, v22
	v_add_u32_e32 v16, s67, v23
	v_ashrrev_i32_e32 v17, 31, v16
	v_add_u32_e32 v12, s66, v23
	v_lshlrev_b32_e32 v4, 4, v22
	v_lshlrev_b64 v[16:17], 11, v[16:17]
	v_ashrrev_i32_e32 v0, 13, v12
	v_and_b32_e32 v1, 0x1fff, v12
	v_and_b32_e32 v96, 0x70, v4
	v_add_u32_e32 v4, 32, v12
	v_add_u32_e32 v8, 64, v12
	v_add_u32_e32 v12, 0x60, v12
	v_lshl_add_u64 v[18:19], s[40:41], 0, v[16:17]
	v_ashrrev_i32_e32 v5, 13, v4
	v_ashrrev_i32_e32 v9, 13, v8
	v_ashrrev_i32_e32 v13, 13, v12
	v_lshl_add_u64 v[18:19], v[18:19], 0, v[96:97]
	v_mul_i32_i24_e32 v0, 0x2010, v0
	v_mul_i32_i24_e32 v5, 0x2010, v5
	v_and_b32_e32 v4, 0x1fff, v4
	v_mul_i32_i24_e32 v9, 0x2010, v9
	v_and_b32_e32 v8, 0x1fff, v8
	v_mul_i32_i24_e32 v13, 0x2010, v13
	v_and_b32_e32 v12, 0x1fff, v12
	v_add_co_u32_e32 v20, vcc, s2, v18
	v_add3_u32 v0, v1, v0, 16
	v_add3_u32 v4, v4, v5, 16
	v_add3_u32 v8, v8, v9, 16
	v_add3_u32 v12, v12, v13, 16
	v_addc_co_u32_e32 v21, vcc, 0, v19, vcc
	v_ashrrev_i32_e32 v1, 31, v0
	v_ashrrev_i32_e32 v5, 31, v4
	v_ashrrev_i32_e32 v9, 31, v8
	v_ashrrev_i32_e32 v13, 31, v12
	global_load_dwordx4 v[72:75], v[18:19], off
	global_load_dwordx4 v[84:87], v[20:21], off
	v_add_co_u32_e32 v20, vcc, s52, v18
	v_lshlrev_b64 v[0:1], 11, v[0:1]
	v_lshlrev_b64 v[4:5], 11, v[4:5]
	v_lshlrev_b64 v[8:9], 11, v[8:9]
	v_lshlrev_b64 v[12:13], 11, v[12:13]
	v_addc_co_u32_e32 v21, vcc, 0, v19, vcc
	v_lshl_add_u64 v[2:3], s[48:49], 0, v[0:1]
	v_lshl_add_u64 v[6:7], s[48:49], 0, v[4:5]
	v_lshl_add_u64 v[10:11], s[48:49], 0, v[8:9]
	v_lshl_add_u64 v[14:15], s[48:49], 0, v[12:13]
	v_add_co_u32_e32 v18, vcc, s53, v18
	v_lshl_add_u64 v[2:3], v[2:3], 0, v[96:97]
	v_lshl_add_u64 v[6:7], v[6:7], 0, v[96:97]
	v_lshl_add_u64 v[10:11], v[10:11], 0, v[96:97]
	v_lshl_add_u64 v[14:15], v[14:15], 0, v[96:97]
	v_addc_co_u32_e32 v19, vcc, 0, v19, vcc
	global_load_dwordx4 v[88:91], v[20:21], off
	global_load_dwordx4 v[92:95], v[18:19], off
	global_load_dwordx4 v[64:67], v[2:3], off
	global_load_dwordx4 v[68:71], v[6:7], off
	global_load_dwordx4 v[76:79], v[10:11], off
	global_load_dwordx4 v[80:83], v[14:15], off
	v_mul_lo_u32 v7, v23, s54
	v_add3_u32 v98, 16, v7, v96
	v_and_b32_e32 v2, 31, v22
	v_lshrrev_b32_e32 v3, 1, v22
	v_and_b32_e32 v6, 0x5f, v22
	v_and_or_b32 v2, v3, s55, v2
	v_or_b32_e32 v0, v0, v96
	v_and_b32_e32 v3, 16, v3
	v_mul_u32_u24_e32 v6, 0x90, v6
	v_mul_lo_u32 v2, v2, s54
	v_lshl_add_u64 v[100:101], s[46:47], 0, v[0:1]
	v_or_b32_e32 v4, v4, v96
	v_or_b32_e32 v8, v8, v96
	v_or_b32_e32 v12, v12, v96
	v_or_b32_e32 v16, v16, v96
	v_mov_b32_e32 v0, 0
	s_mov_b32 s10, 0
	v_add3_u32 v115, 16, v6, v3
	v_add3_u32 v116, 16, v2, v3
	v_lshl_add_u64 v[102:103], s[46:47], 0, v[4:5]
	v_lshl_add_u64 v[104:105], s[46:47], 0, v[8:9]
	v_lshl_add_u64 v[106:107], s[46:47], 0, v[12:13]
	v_lshl_add_u64 v[108:109], s[48:49], 0, v[16:17]
	s_mov_b64 s[6:7], 0
	v_mov_b32_e32 v1, v0
	v_mov_b32_e32 v2, v0
	v_mov_b32_e32 v3, v0
	v_mov_b32_e32 v4, v0
	v_mov_b32_e32 v5, v0
	v_mov_b32_e32 v6, v0
	v_mov_b32_e32 v7, v0
	v_lshl_add_u64 v[238:239], v[100:101], 0, s[6:7]
	v_lshl_add_u64 v[240:241], v[102:103], 0, s[6:7]
	global_load_dwordx4 v[222:225], v[238:239], off
	global_load_dwordx4 v[226:229], v[240:241], off
	v_lshl_add_u64 v[238:239], v[104:105], 0, s[6:7]
	v_lshl_add_u64 v[248:249], v[108:109], 0, s[6:7]
	v_lshl_add_u64 v[240:241], v[106:107], 0, s[6:7]
	global_load_dwordx4 v[230:233], v[238:239], off
	global_load_dwordx4 v[234:237], v[240:241], off
	v_add_co_u32_e32 v238, vcc, 0x2010000, v248
	s_nop 1
	v_addc_co_u32_e32 v239, vcc, 0, v249, vcc
	v_add_co_u32_e32 v242, vcc, 0x2020000, v248
	s_nop 1
	v_addc_co_u32_e32 v243, vcc, 0, v249, vcc
	v_add_co_u32_e32 v250, vcc, 0x2030000, v248
	global_load_dwordx4 v[238:241], v[238:239], off offset:128
	s_nop 0
	global_load_dwordx4 v[242:245], v[242:243], off offset:128
	v_addc_co_u32_e32 v251, vcc, 0, v249, vcc
	v_add_co_u32_e32 v252, vcc, 0x2040000, v248
	s_nop 1
	v_addc_co_u32_e32 v253, vcc, 0, v249, vcc
	global_load_dwordx4 v[248:251], v[250:251], off offset:128
	s_nop 0
	global_load_dwordx4 v[252:255], v[252:253], off offset:128
	s_waitcnt vmcnt(15)
	ds_write_b128 v98, v[72:75] offset:36864
	s_waitcnt vmcnt(14)
	ds_write_b128 v98, v[84:87] offset:41472
	s_waitcnt vmcnt(13)
	ds_write_b128 v98, v[88:91] offset:46080
	s_waitcnt vmcnt(12)
	ds_write_b128 v98, v[92:95] offset:50688
	s_waitcnt vmcnt(11)
	ds_write_b128 v98, v[64:67]
	s_waitcnt vmcnt(10)
	ds_write_b128 v98, v[68:71] offset:4608
	s_waitcnt vmcnt(9)
	ds_write_b128 v98, v[76:79] offset:9216
	s_waitcnt vmcnt(8)
	ds_write_b128 v98, v[80:83] offset:13824
	s_waitcnt lgkmcnt(0)
	s_barrier
	v_mov_b32_e32 v8, v0
	v_mov_b32_e32 v9, v0
	v_mov_b32_e32 v10, v0
	v_mov_b32_e32 v11, v0
	v_mov_b32_e32 v12, v0
	v_mov_b32_e32 v13, v0
	v_mov_b32_e32 v14, v0
	v_mov_b32_e32 v15, v0
	v_mov_b32_e32 v16, v0
	v_mov_b32_e32 v17, v0
	v_mov_b32_e32 v18, v0
	v_mov_b32_e32 v19, v0
	v_mov_b32_e32 v20, v0
	v_mov_b32_e32 v21, v0
	v_mov_b32_e32 v22, v0
	v_mov_b32_e32 v23, v0
	v_mov_b32_e32 v24, v0
	v_mov_b32_e32 v25, v0
	v_mov_b32_e32 v26, v0
	v_mov_b32_e32 v27, v0
	v_mov_b32_e32 v28, v0
	v_mov_b32_e32 v29, v0
	v_mov_b32_e32 v30, v0
	v_mov_b32_e32 v31, v0
	v_mov_b32_e32 v32, v0
	v_mov_b32_e32 v33, v0
	v_mov_b32_e32 v34, v0
	v_mov_b32_e32 v35, v0
	v_mov_b32_e32 v36, v0
	v_mov_b32_e32 v37, v0
	v_mov_b32_e32 v38, v0
	v_mov_b32_e32 v39, v0
	v_mov_b32_e32 v40, v0
	v_mov_b32_e32 v41, v0
	v_mov_b32_e32 v42, v0
	v_mov_b32_e32 v43, v0
	v_mov_b32_e32 v44, v0
	v_mov_b32_e32 v45, v0
	v_mov_b32_e32 v46, v0
	v_mov_b32_e32 v47, v0
	v_mov_b32_e32 v48, v0
	v_mov_b32_e32 v49, v0
	v_mov_b32_e32 v50, v0
	v_mov_b32_e32 v51, v0
	v_mov_b32_e32 v52, v0
	v_mov_b32_e32 v53, v0
	v_mov_b32_e32 v54, v0
	v_mov_b32_e32 v55, v0
	v_mov_b32_e32 v56, v0
	v_mov_b32_e32 v57, v0
	v_mov_b32_e32 v58, v0
	v_mov_b32_e32 v59, v0
	v_mov_b32_e32 v60, v0
	v_mov_b32_e32 v61, v0
	v_mov_b32_e32 v62, v0
	v_mov_b32_e32 v63, v0
	s_branch .LBB0_369
; __device__ __forceinline__ f32x16 mfma32(bf16x8 a, bf16x8 b, f32x16 c) { return __builtin_amdgcn_mfma_f32_32x32x16_bf16(a, b, c, 0, 0, 0); }
; template <class ARowF, class KOffF>
; __device__ __forceinline__ void gemm_kloop(f32x16 (&acc)[2][2], ARowF arow, KOffF koff, const u16* __restrict__ Bt, int m0, int n0, unsigned char* smem) {
;     ...
;   for (int kt = 0; kt < 16; ++kt) {
;     const int buf = kt & 1;
;     if (kt + 1 < 16) {
;       const size_t ko = koff((kt + 1) * 64); const int kb = (kt + 1) * 64;
;       ra0 = *(const u32x4*)(pa0 + ko); ra1 = *(const u32x4*)(pa1 + ko); ra2 = *(const u32x4*)(pa2 + ko); ra3 = *(const u32x4*)(pa3 + ko);
;       rb0 = *(const u32x4*)(pb0 + kb); rb1 = *(const u32x4*)(pb0 + 32 * 1024 + kb); rb2 = *(const u32x4*)(pb0 + 64 * 1024 + kb); rb3 = *(const u32x4*)(pb0 + 96 * 1024 + kb);
;     }
;     const u16* cA = sA + buf * 128 * 72 + (wm * 64 + l31) * 72 + hf * 8;
;     const u16* cB = sB + buf * 128 * 72 + (wn * 64 + l31) * 72 + hf * 8;
; #pragma unroll
;     for (int ks = 0; ks < 4; ++ks) {
;       bf16x8 a0 = *(const bf16x8*)(cA + ks * 16);
;       bf16x8 a1 = *(const bf16x8*)(cA + 32 * 72 + ks * 16);
;       bf16x8 b0 = *(const bf16x8*)(cB + ks * 16);
;       bf16x8 b1 = *(const bf16x8*)(cB + 32 * 72 + ks * 16);
;       acc[0][0] = mfma32(a0, b0, acc[0][0]);
;       acc[0][1] = mfma32(a0, b1, acc[0][1]);
;       acc[1][0] = mfma32(a1, b0, acc[1][0]);
;       acc[1][1] = mfma32(a1, b1, acc[1][1]);
.LBB0_369:
.Lgemm_p4_loop:
	v_lshl_add_u64 v[72:73], v[100:101], 0, s[6:7]
	v_lshl_add_u64 v[74:75], v[102:103], 0, s[6:7]
	global_load_dwordx4 v[64:67], v[72:73], off offset:128
	global_load_dwordx4 v[68:71], v[74:75], off offset:128
	v_lshl_add_u64 v[72:73], v[104:105], 0, s[6:7]
	v_lshl_add_u64 v[88:89], v[108:109], 0, s[6:7]
	v_lshl_add_u64 v[74:75], v[106:107], 0, s[6:7]
	global_load_dwordx4 v[76:79], v[72:73], off offset:128
	global_load_dwordx4 v[80:83], v[74:75], off offset:128
	v_add_co_u32_e32 v72, vcc, 0x2010000, v88
	s_nop 1
	v_addc_co_u32_e32 v73, vcc, 0, v89, vcc
	v_add_co_u32_e32 v84, vcc, 0x2020000, v88
	s_nop 1
	v_addc_co_u32_e32 v85, vcc, 0, v89, vcc
	v_add_co_u32_e32 v90, vcc, 0x2030000, v88
	global_load_dwordx4 v[72:75], v[72:73], off offset:256
	s_nop 0
	global_load_dwordx4 v[84:87], v[84:85], off offset:256
	v_addc_co_u32_e32 v91, vcc, 0, v89, vcc
	v_add_co_u32_e32 v92, vcc, 0x2040000, v88
	s_nop 1
	v_addc_co_u32_e32 v93, vcc, 0, v89, vcc
	global_load_dwordx4 v[88:91], v[90:91], off offset:256
	s_nop 0
	global_load_dwordx4 v[92:95], v[92:93], off offset:256
	ds_read_b128 v[118:121], v116
	ds_read_b128 v[122:125], v115 offset:36864
	ds_read_b128 v[126:129], v116 offset:32
	ds_read_b128 v[130:133], v115 offset:36896
	ds_read_b128 v[134:137], v115 offset:41472
	ds_read_b128 v[138:141], v115 offset:41504
	s_waitcnt lgkmcnt(4)
	v_mfma_f32_32x32x16_bf16 v[48:63], v[118:121], v[122:125], v[48:63]
	s_waitcnt lgkmcnt(1)
	v_mfma_f32_32x32x16_bf16 v[32:47], v[118:121], v[134:137], v[32:47]
	ds_read_b128 v[118:121], v116 offset:4608
	ds_read_b128 v[142:145], v116 offset:4640
	s_waitcnt lgkmcnt(1)
	v_mfma_f32_32x32x16_bf16 v[16:31], v[118:121], v[122:125], v[16:31]
	v_mfma_f32_32x32x16_bf16 v[0:15], v[118:121], v[134:137], v[0:15]
	v_mfma_f32_32x32x16_bf16 v[48:63], v[126:129], v[130:133], v[48:63]
	v_mfma_f32_32x32x16_bf16 v[32:47], v[126:129], v[138:141], v[32:47]
	s_waitcnt lgkmcnt(0)
	v_mfma_f32_32x32x16_bf16 v[16:31], v[142:145], v[130:133], v[16:31]
	ds_read_b128 v[118:121], v116 offset:64
	ds_read_b128 v[122:125], v115 offset:36928
	ds_read_b128 v[126:129], v116 offset:96
	ds_read_b128 v[130:133], v115 offset:36960
	v_mfma_f32_32x32x16_bf16 v[0:15], v[142:145], v[138:141], v[0:15]
	ds_read_b128 v[134:137], v115 offset:41536
	ds_read_b128 v[138:141], v115 offset:41568
	s_waitcnt lgkmcnt(4)
	v_mfma_f32_32x32x16_bf16 v[48:63], v[118:121], v[122:125], v[48:63]
	s_waitcnt lgkmcnt(1)
	v_mfma_f32_32x32x16_bf16 v[32:47], v[118:121], v[134:137], v[32:47]
	ds_read_b128 v[118:121], v116 offset:4672
	ds_read_b128 v[142:145], v116 offset:4704
	s_waitcnt lgkmcnt(1)
	v_mfma_f32_32x32x16_bf16 v[16:31], v[118:121], v[122:125], v[16:31]
	v_mfma_f32_32x32x16_bf16 v[0:15], v[118:121], v[134:137], v[0:15]
	v_mfma_f32_32x32x16_bf16 v[48:63], v[126:129], v[130:133], v[48:63]
	v_mfma_f32_32x32x16_bf16 v[32:47], v[126:129], v[138:141], v[32:47]
	s_waitcnt lgkmcnt(0)
	v_mfma_f32_32x32x16_bf16 v[16:31], v[142:145], v[130:133], v[16:31]
	v_mfma_f32_32x32x16_bf16 v[0:15], v[142:145], v[138:141], v[0:15]
	v_add_u32_e32 v96, 18432, v98
	s_waitcnt vmcnt(15)
	ds_write_b128 v96, v[222:225]
	s_waitcnt vmcnt(14)
	ds_write_b128 v96, v[226:229] offset:4608
	s_waitcnt vmcnt(13)
	ds_write_b128 v96, v[230:233] offset:9216
	s_waitcnt vmcnt(12)
	ds_write_b128 v96, v[234:237] offset:13824
	s_waitcnt vmcnt(11)
	ds_write_b128 v96, v[238:241] offset:36864
	s_waitcnt vmcnt(10)
	ds_write_b128 v96, v[242:245] offset:41472
	s_waitcnt vmcnt(9)
	ds_write_b128 v96, v[248:251] offset:46080
	s_waitcnt vmcnt(8)
	ds_write_b128 v96, v[252:255] offset:50688
	s_waitcnt lgkmcnt(0)
	s_barrier
	v_lshl_add_u64 v[238:239], v[100:101], 0, s[6:7]
	v_lshl_add_u64 v[240:241], v[102:103], 0, s[6:7]
	global_load_dwordx4 v[222:225], v[238:239], off offset:256
	global_load_dwordx4 v[226:229], v[240:241], off offset:256
	v_lshl_add_u64 v[238:239], v[104:105], 0, s[6:7]
	v_lshl_add_u64 v[248:249], v[108:109], 0, s[6:7]
	v_lshl_add_u64 v[240:241], v[106:107], 0, s[6:7]
	global_load_dwordx4 v[230:233], v[238:239], off offset:256
	global_load_dwordx4 v[234:237], v[240:241], off offset:256
	v_add_co_u32_e32 v238, vcc, 0x2010000, v248
	s_nop 1
	v_addc_co_u32_e32 v239, vcc, 0, v249, vcc
	v_add_co_u32_e32 v242, vcc, 0x2020000, v248
	s_nop 1
	v_addc_co_u32_e32 v243, vcc, 0, v249, vcc
	v_add_co_u32_e32 v250, vcc, 0x2030000, v248
	global_load_dwordx4 v[238:241], v[238:239], off offset:384
	s_nop 0
	global_load_dwordx4 v[242:245], v[242:243], off offset:384
	v_addc_co_u32_e32 v251, vcc, 0, v249, vcc
	v_add_co_u32_e32 v252, vcc, 0x2040000, v248
	s_nop 1
	v_addc_co_u32_e32 v253, vcc, 0, v249, vcc
	global_load_dwordx4 v[248:251], v[250:251], off offset:384
	s_nop 0
	global_load_dwordx4 v[252:255], v[252:253], off offset:384
	ds_read_b128 v[118:121], v116 offset:18432
	ds_read_b128 v[122:125], v115 offset:55296
	ds_read_b128 v[126:129], v116 offset:18464
	ds_read_b128 v[130:133], v115 offset:55328
	ds_read_b128 v[134:137], v115 offset:59904
	ds_read_b128 v[138:141], v115 offset:59936
	s_waitcnt lgkmcnt(4)
	v_mfma_f32_32x32x16_bf16 v[48:63], v[118:121], v[122:125], v[48:63]
	s_waitcnt lgkmcnt(1)
	v_mfma_f32_32x32x16_bf16 v[32:47], v[118:121], v[134:137], v[32:47]
	ds_read_b128 v[118:121], v116 offset:23040
	ds_read_b128 v[142:145], v116 offset:23072
	s_waitcnt lgkmcnt(1)
	v_mfma_f32_32x32x16_bf16 v[16:31], v[118:121], v[122:125], v[16:31]
	v_mfma_f32_32x32x16_bf16 v[0:15], v[118:121], v[134:137], v[0:15]
	v_mfma_f32_32x32x16_bf16 v[48:63], v[126:129], v[130:133], v[48:63]
	v_mfma_f32_32x32x16_bf16 v[32:47], v[126:129], v[138:141], v[32:47]
	s_waitcnt lgkmcnt(0)
; __device__ __forceinline__ f32x16 mfma32(bf16x8 a, bf16x8 b, f32x16 c) { return __builtin_amdgcn_mfma_f32_32x32x16_bf16(a, b, c, 0, 0, 0); }
; __device__ __forceinline__ void lds_barrier() { asm volatile("s_waitcnt lgkmcnt(0)\n\ts_barrier" ::: "memory"); }
; template <class ARowF, class KOffF>
; __device__ __forceinline__ void gemm_kloop(f32x16 (&acc)[2][2], ARowF arow, KOffF koff, const u16* __restrict__ Bt, int m0, int n0, unsigned char* smem) {
;     ...
;   for (int kt = 0; kt < 16; ++kt) {
;     const int buf = kt & 1;
;     if (kt + 1 < 16) {
;       const size_t ko = koff((kt + 1) * 64); const int kb = (kt + 1) * 64;
;       ra0 = *(const u32x4*)(pa0 + ko); ra1 = *(const u32x4*)(pa1 + ko); ra2 = *(const u32x4*)(pa2 + ko); ra3 = *(const u32x4*)(pa3 + ko);
;       rb0 = *(const u32x4*)(pb0 + kb); rb1 = *(const u32x4*)(pb0 + 32 * 1024 + kb); rb2 = *(const u32x4*)(pb0 + 64 * 1024 + kb); rb3 = *(const u32x4*)(pb0 + 96 * 1024 + kb);
;     }
;     const u16* cA = sA + buf * 128 * 72 + (wm * 64 + l31) * 72 + hf * 8;
;     const u16* cB = sB + buf * 128 * 72 + (wn * 64 + l31) * 72 + hf * 8;
; #pragma unroll
;     for (int ks = 0; ks < 4; ++ks) {
;       bf16x8 a0 = *(const bf16x8*)(cA + ks * 16);
;       bf16x8 a1 = *(const bf16x8*)(cA + 32 * 72 + ks * 16);
;       bf16x8 b0 = *(const bf16x8*)(cB + ks * 16);
;       bf16x8 b1 = *(const bf16x8*)(cB + 32 * 72 + ks * 16);
;       acc[0][0] = mfma32(a0, b0, acc[0][0]);
;       acc[0][1] = mfma32(a0, b1, acc[0][1]);
;       acc[1][0] = mfma32(a1, b0, acc[1][0]);
;       acc[1][1] = mfma32(a1, b1, acc[1][1]);
;     }
;     if (kt + 1 < 16) {
;       u16* wA = wA0 + (buf ^ 1) * 128 * 72; u16* wB = wB0 + (buf ^ 1) * 128 * 72;
;       *(u32x4*)(wA) = ra0; *(u32x4*)(wA + 32 * 72) = ra1; *(u32x4*)(wA + 64 * 72) = ra2; *(u32x4*)(wA + 96 * 72) = ra3;
;       *(u32x4*)(wB) = rb0; *(u32x4*)(wB + 32 * 72) = rb1; *(u32x4*)(wB + 64 * 72) = rb2; *(u32x4*)(wB + 96 * 72) = rb3;
;     }
;     lds_barrier();
;   }
	v_mfma_f32_32x32x16_bf16 v[16:31], v[142:145], v[130:133], v[16:31]
	ds_read_b128 v[118:121], v116 offset:18496
	ds_read_b128 v[122:125], v115 offset:55360
	ds_read_b128 v[126:129], v116 offset:18528
	ds_read_b128 v[130:133], v115 offset:55392
	v_mfma_f32_32x32x16_bf16 v[0:15], v[142:145], v[138:141], v[0:15]
	ds_read_b128 v[134:137], v115 offset:59968
	ds_read_b128 v[138:141], v115 offset:60000
	s_waitcnt lgkmcnt(4)
	v_mfma_f32_32x32x16_bf16 v[48:63], v[118:121], v[122:125], v[48:63]
	s_waitcnt lgkmcnt(1)
	v_mfma_f32_32x32x16_bf16 v[32:47], v[118:121], v[134:137], v[32:47]
	ds_read_b128 v[118:121], v116 offset:23104
	ds_read_b128 v[142:145], v116 offset:23136
	s_waitcnt lgkmcnt(1)
	v_mfma_f32_32x32x16_bf16 v[16:31], v[118:121], v[122:125], v[16:31]
	v_mfma_f32_32x32x16_bf16 v[0:15], v[118:121], v[134:137], v[0:15]
	v_mfma_f32_32x32x16_bf16 v[48:63], v[126:129], v[130:133], v[48:63]
	v_mfma_f32_32x32x16_bf16 v[32:47], v[126:129], v[138:141], v[32:47]
	s_waitcnt lgkmcnt(0)
	v_mfma_f32_32x32x16_bf16 v[16:31], v[142:145], v[130:133], v[16:31]
	v_mfma_f32_32x32x16_bf16 v[0:15], v[142:145], v[138:141], v[0:15]
	v_mov_b32_e32 v96, v98
	s_waitcnt vmcnt(15)
	ds_write_b128 v96, v[64:67]
	s_waitcnt vmcnt(14)
	ds_write_b128 v96, v[68:71] offset:4608
	s_waitcnt vmcnt(13)
	ds_write_b128 v96, v[76:79] offset:9216
	s_waitcnt vmcnt(12)
	ds_write_b128 v96, v[80:83] offset:13824
	s_waitcnt vmcnt(11)
	ds_write_b128 v96, v[72:75] offset:36864
	s_waitcnt vmcnt(10)
	ds_write_b128 v96, v[84:87] offset:41472
	s_waitcnt vmcnt(9)
	ds_write_b128 v96, v[88:91] offset:46080
	s_waitcnt vmcnt(8)
	ds_write_b128 v96, v[92:95] offset:50688
	s_waitcnt lgkmcnt(0)
	s_barrier
	s_add_u32 s6, s6, 0x100
	s_addc_u32 s7, s7, 0
	s_cmpk_lg_i32 s6, 0x700
	s_cbranch_scc1 .Lgemm_p4_loop
	ds_read_b128 v[118:121], v116
	ds_read_b128 v[122:125], v115 offset:36864
	ds_read_b128 v[126:129], v116 offset:32
	ds_read_b128 v[130:133], v115 offset:36896
	ds_read_b128 v[134:137], v115 offset:41472
	ds_read_b128 v[138:141], v115 offset:41504
	s_waitcnt lgkmcnt(4)
	v_mfma_f32_32x32x16_bf16 v[48:63], v[118:121], v[122:125], v[48:63]
	s_waitcnt lgkmcnt(1)
	v_mfma_f32_32x32x16_bf16 v[32:47], v[118:121], v[134:137], v[32:47]
	ds_read_b128 v[118:121], v116 offset:4608
	ds_read_b128 v[142:145], v116 offset:4640
	s_waitcnt lgkmcnt(1)
	v_mfma_f32_32x32x16_bf16 v[16:31], v[118:121], v[122:125], v[16:31]
	v_mfma_f32_32x32x16_bf16 v[0:15], v[118:121], v[134:137], v[0:15]
	v_mfma_f32_32x32x16_bf16 v[48:63], v[126:129], v[130:133], v[48:63]
	v_mfma_f32_32x32x16_bf16 v[32:47], v[126:129], v[138:141], v[32:47]
	s_waitcnt lgkmcnt(0)
	v_mfma_f32_32x32x16_bf16 v[16:31], v[142:145], v[130:133], v[16:31]
	ds_read_b128 v[118:121], v116 offset:64
	ds_read_b128 v[122:125], v115 offset:36928
	ds_read_b128 v[126:129], v116 offset:96
	ds_read_b128 v[130:133], v115 offset:36960
	v_mfma_f32_32x32x16_bf16 v[0:15], v[142:145], v[138:141], v[0:15]
	ds_read_b128 v[134:137], v115 offset:41536
	ds_read_b128 v[138:141], v115 offset:41568
	s_waitcnt lgkmcnt(4)
	v_mfma_f32_32x32x16_bf16 v[48:63], v[118:121], v[122:125], v[48:63]
	s_waitcnt lgkmcnt(1)
	v_mfma_f32_32x32x16_bf16 v[32:47], v[118:121], v[134:137], v[32:47]
	ds_read_b128 v[118:121], v116 offset:4672
	ds_read_b128 v[142:145], v116 offset:4704
	s_waitcnt lgkmcnt(1)
	v_mfma_f32_32x32x16_bf16 v[16:31], v[118:121], v[122:125], v[16:31]
	v_mfma_f32_32x32x16_bf16 v[0:15], v[118:121], v[134:137], v[0:15]
	v_mfma_f32_32x32x16_bf16 v[48:63], v[126:129], v[130:133], v[48:63]
	v_mfma_f32_32x32x16_bf16 v[32:47], v[126:129], v[138:141], v[32:47]
	s_waitcnt lgkmcnt(0)
	v_mfma_f32_32x32x16_bf16 v[16:31], v[142:145], v[130:133], v[16:31]
	v_mfma_f32_32x32x16_bf16 v[0:15], v[142:145], v[138:141], v[0:15]
	v_add_u32_e32 v96, 18432, v98
	s_waitcnt vmcnt(7)
	ds_write_b128 v96, v[222:225]
	s_waitcnt vmcnt(6)
	ds_write_b128 v96, v[226:229] offset:4608
	s_waitcnt vmcnt(5)
	ds_write_b128 v96, v[230:233] offset:9216
	s_waitcnt vmcnt(4)
	ds_write_b128 v96, v[234:237] offset:13824
	s_waitcnt vmcnt(3)
	ds_write_b128 v96, v[238:241] offset:36864
	s_waitcnt vmcnt(2)
	ds_write_b128 v96, v[242:245] offset:41472
	s_waitcnt vmcnt(1)
	ds_write_b128 v96, v[248:251] offset:46080
	s_waitcnt vmcnt(0)
	ds_write_b128 v96, v[252:255] offset:50688
	s_waitcnt lgkmcnt(0)
	s_barrier
	ds_read_b128 v[118:121], v116 offset:18432
	ds_read_b128 v[122:125], v115 offset:55296
	ds_read_b128 v[126:129], v116 offset:18464
	ds_read_b128 v[130:133], v115 offset:55328
	ds_read_b128 v[134:137], v115 offset:59904
	ds_read_b128 v[138:141], v115 offset:59936
	s_waitcnt lgkmcnt(4)
	v_mfma_f32_32x32x16_bf16 v[48:63], v[118:121], v[122:125], v[48:63]
	s_waitcnt lgkmcnt(1)
	v_mfma_f32_32x32x16_bf16 v[32:47], v[118:121], v[134:137], v[32:47]
	ds_read_b128 v[118:121], v116 offset:23040
	ds_read_b128 v[142:145], v116 offset:23072
	s_waitcnt lgkmcnt(1)
	v_mfma_f32_32x32x16_bf16 v[16:31], v[118:121], v[122:125], v[16:31]
	v_mfma_f32_32x32x16_bf16 v[0:15], v[118:121], v[134:137], v[0:15]
	v_mfma_f32_32x32x16_bf16 v[48:63], v[126:129], v[130:133], v[48:63]
	v_mfma_f32_32x32x16_bf16 v[32:47], v[126:129], v[138:141], v[32:47]
	s_waitcnt lgkmcnt(0)
	v_mfma_f32_32x32x16_bf16 v[16:31], v[142:145], v[130:133], v[16:31]
	ds_read_b128 v[118:121], v116 offset:18496
	ds_read_b128 v[122:125], v115 offset:55360
	ds_read_b128 v[126:129], v116 offset:18528
	ds_read_b128 v[130:133], v115 offset:55392
	v_mfma_f32_32x32x16_bf16 v[0:15], v[142:145], v[138:141], v[0:15]
	ds_read_b128 v[134:137], v115 offset:59968
	ds_read_b128 v[138:141], v115 offset:60000
	s_waitcnt lgkmcnt(4)
	v_mfma_f32_32x32x16_bf16 v[48:63], v[118:121], v[122:125], v[48:63]
	s_waitcnt lgkmcnt(1)
	v_mfma_f32_32x32x16_bf16 v[32:47], v[118:121], v[134:137], v[32:47]
	ds_read_b128 v[118:121], v116 offset:23104
	ds_read_b128 v[142:145], v116 offset:23136
	s_waitcnt lgkmcnt(1)
	v_mfma_f32_32x32x16_bf16 v[16:31], v[118:121], v[122:125], v[16:31]
	v_mfma_f32_32x32x16_bf16 v[0:15], v[118:121], v[134:137], v[0:15]
	v_mfma_f32_32x32x16_bf16 v[48:63], v[126:129], v[130:133], v[48:63]
	v_mfma_f32_32x32x16_bf16 v[32:47], v[126:129], v[138:141], v[32:47]
	s_waitcnt lgkmcnt(0)
	v_mfma_f32_32x32x16_bf16 v[16:31], v[142:145], v[130:133], v[16:31]
	v_mfma_f32_32x32x16_bf16 v[0:15], v[142:145], v[138:141], v[0:15]
	s_waitcnt lgkmcnt(0)
	s_barrier
	s_nop 5

; __device__ __forceinline__ void lds_barrier() { asm volatile("s_waitcnt lgkmcnt(0)\n\ts_barrier" ::: "memory"); }
; __device__ __forceinline__ bool tile_map(int i, int xcd, int MT, int NT, int& mt, int& nt) {
;   int cm = (MT - xcd + 7) >> 3;
;   int ag = i / (8 * NT);
;   if (ag * 8 >= cm) return false;
;   int gs = cm - ag * 8; if (gs > 8) gs = 8;
;   int j = i - ag * 8 * NT;
;   if (j >= gs * NT) return false;
;   int al = j % gs; nt = j / gs;
;   mt = xcd + 8 * (8 * ag + al);
;   return true;
; template <class ARowF, class KOffF>
; __device__ __forceinline__ void gemm_kloop(f32x16 (&acc)[2][2], ARowF arow, KOffF koff, const u16* __restrict__ Bt, int m0, int n0, unsigned char* smem) {
;     ...
;   const u16* pa0 = arow(m0 + lr) + lc * 8; const u16* pa1 = arow(m0 + lr + 32) + lc * 8;
;   const u16* pa2 = arow(m0 + lr + 64) + lc * 8; const u16* pa3 = arow(m0 + lr + 96) + lc * 8;
;   const u16* pb0 = Bt + (size_t)(n0 + lr) * 1024 + lc * 8;
;   u32x4 ra0, ra1, ra2, ra3, rb0, rb1, rb2, rb3;
;   {
;     const size_t ko = koff(0);
;     ra0 = *(const u32x4*)(pa0 + ko); ra1 = *(const u32x4*)(pa1 + ko); ra2 = *(const u32x4*)(pa2 + ko); ra3 = *(const u32x4*)(pa3 + ko);
;     rb0 = *(const u32x4*)(pb0); rb1 = *(const u32x4*)(pb0 + 32 * 1024); rb2 = *(const u32x4*)(pb0 + 64 * 1024); rb3 = *(const u32x4*)(pb0 + 96 * 1024);
;   }
;   u16* wA0 = sA + lr * 72 + lc * 8; u16* wB0 = sB + lr * 72 + lc * 8;
;   *(u32x4*)(wA0) = ra0; *(u32x4*)(wA0 + 32 * 72) = ra1; *(u32x4*)(wA0 + 64 * 72) = ra2; *(u32x4*)(wA0 + 96 * 72) = ra3;
;   *(u32x4*)(wB0) = rb0; *(u32x4*)(wB0 + 32 * 72) = rb1; *(u32x4*)(wB0 + 64 * 72) = rb2; *(u32x4*)(wB0 + 96 * 72) = rb3;
;   lds_barrier();
.LBB0_396:
	s_sub_i32 s14, 16, s16
	s_min_u32 s17, s14, 8
	s_lshl_b32 s14, s16, 3
	s_sub_i32 s26, s25, s14
	s_lshl_b32 s14, s17, 3
	s_cmp_ge_i32 s26, s14
	s_mov_b64 s[14:15], -1
	s_cbranch_scc1 .LBB0_395
	v_cvt_f32_u32_e32 v0, s17
	s_sub_i32 s27, 0, s17
	s_abs_i32 s15, s26
	s_ashr_i32 s14, s26, 31
	v_rcp_iflag_f32_e32 v0, v0
	v_mov_b32_e32 v20, v218
	v_mul_f32_e32 v0, 0x4f7ffffe, v0
	v_cvt_u32_f32_e32 v0, v0
	v_ashrrev_i32_e32 v21, 3, v20
	v_lshlrev_b32_e32 v2, 4, v20
	v_and_b32_e32 v96, 0x70, v2
	v_readfirstlane_b32 s28, v0
	s_mul_i32 s27, s27, s28
	s_mul_hi_u32 s27, s28, s27
	s_add_i32 s28, s28, s27
	s_mul_hi_u32 s27, s15, s28
	s_mul_i32 s28, s27, s17
	s_sub_i32 s15, s15, s28
	s_add_i32 s29, s27, 1
	s_sub_i32 s28, s15, s17
	s_cmp_ge_u32 s15, s17
	s_cselect_b32 s27, s29, s27
	s_cselect_b32 s15, s28, s15
	s_add_i32 s28, s27, 1
	s_cmp_ge_u32 s15, s17
	s_cselect_b32 s15, s28, s27
	s_xor_b32 s15, s15, s14
	s_sub_i32 s14, s15, s14
	s_mul_i32 s15, s14, s17
	s_lshl_b32 s27, s14, 7
	s_sub_i32 s14, s26, s15
	s_add_i32 s14, s14, s16
	s_lshl_b32 s14, s14, 10
	s_or_b32 s26, s14, s2
	v_add_u32_e32 v14, s27, v21
	v_add_u32_e32 v10, s26, v21
	v_ashrrev_i32_e32 v15, 31, v14
	v_ashrrev_i32_e32 v0, 13, v10
	v_lshlrev_b64 v[14:15], 11, v[14:15]
	v_mul_i32_i24_e32 v22, 0x2010, v0
	v_and_b32_e32 v0, 0x1fff, v10
	v_add_u32_e32 v2, 32, v10
	v_add_u32_e32 v6, 64, v10
	v_add_u32_e32 v10, 0x60, v10
	v_lshl_add_u64 v[16:17], s[10:11], 0, v[14:15]
	v_ashrrev_i32_e32 v3, 13, v2
	v_ashrrev_i32_e32 v7, 13, v6
	v_ashrrev_i32_e32 v11, 13, v10
	v_lshl_add_u64 v[16:17], v[16:17], 0, v[96:97]
	v_mul_i32_i24_e32 v3, 0x2010, v3
	v_and_b32_e32 v2, 0x1fff, v2
	v_mul_i32_i24_e32 v7, 0x2010, v7
	v_and_b32_e32 v6, 0x1fff, v6
	v_mul_i32_i24_e32 v11, 0x2010, v11
	v_and_b32_e32 v10, 0x1fff, v10
	v_add_co_u32_e32 v18, vcc, s19, v16
	v_add3_u32 v0, v0, v22, 16
	v_add3_u32 v2, v2, v3, 16
	v_add3_u32 v6, v6, v7, 16
	v_add3_u32 v10, v10, v11, 16
	v_addc_co_u32_e32 v19, vcc, 0, v17, vcc
	v_ashrrev_i32_e32 v1, 31, v0
	v_ashrrev_i32_e32 v3, 31, v2
	v_ashrrev_i32_e32 v7, 31, v6
	v_ashrrev_i32_e32 v11, 31, v10
	global_load_dwordx4 v[72:75], v[16:17], off
	global_load_dwordx4 v[84:87], v[18:19], off
	v_add_co_u32_e32 v18, vcc, s20, v16
	v_lshlrev_b64 v[0:1], 11, v[0:1]
	v_lshlrev_b64 v[2:3], 11, v[2:3]
	v_lshlrev_b64 v[6:7], 11, v[6:7]
	v_lshlrev_b64 v[10:11], 11, v[10:11]
	v_addc_co_u32_e32 v19, vcc, 0, v17, vcc
	v_lshl_add_u64 v[0:1], s[36:37], 0, v[0:1]
	v_lshl_add_u64 v[4:5], s[36:37], 0, v[2:3]
	v_lshl_add_u64 v[8:9], s[36:37], 0, v[6:7]
	v_lshl_add_u64 v[12:13], s[36:37], 0, v[10:11]
	v_add_co_u32_e32 v16, vcc, s21, v16
	v_lshl_add_u64 v[0:1], v[0:1], 0, v[96:97]
	v_lshl_add_u64 v[4:5], v[4:5], 0, v[96:97]
	v_lshl_add_u64 v[8:9], v[8:9], 0, v[96:97]
	v_lshl_add_u64 v[12:13], v[12:13], 0, v[96:97]
	v_addc_co_u32_e32 v17, vcc, 0, v17, vcc
	global_load_dwordx4 v[88:91], v[18:19], off
	global_load_dwordx4 v[92:95], v[16:17], off
	global_load_dwordx4 v[64:67], v[0:1], off
	global_load_dwordx4 v[68:71], v[4:5], off
	global_load_dwordx4 v[76:79], v[8:9], off
	global_load_dwordx4 v[80:83], v[12:13], off
	v_and_b32_e32 v0, 31, v20
	v_lshrrev_b32_e32 v1, 1, v20
	v_and_or_b32 v0, v1, s23, v0
	v_and_b32_e32 v1, 16, v1
	v_mul_lo_u32 v0, v0, s22
	v_add3_u32 v110, 16, v0, v1
	v_add_u16_e32 v0, s26, v21
	v_and_b32_e32 v4, 0x5f, v20
	v_and_b32_e32 v0, 0x1fff, v0
	v_mul_lo_u32 v5, v21, s22
	v_mul_u32_u24_e32 v4, 0x90, v4
	v_add3_u32 v0, v22, v0, 16
	v_add3_u32 v108, 16, v5, v96
	v_add3_u32 v109, 16, v4, v1
	v_ashrrev_i32_e32 v1, 31, v0
	v_lshlrev_b64 v[0:1], 11, v[0:1]
	v_or_b32_e32 v0, v0, v96
	v_lshl_add_u64 v[98:99], s[12:13], 0, v[0:1]
	v_or_b32_e32 v2, v2, v96
	v_or_b32_e32 v6, v6, v96
	v_or_b32_e32 v10, v10, v96
	v_or_b32_e32 v14, v14, v96
	v_mov_b32_e32 v0, 0
	s_mov_b32 s28, 0
	v_lshl_add_u64 v[100:101], s[12:13], 0, v[2:3]
	v_lshl_add_u64 v[102:103], s[12:13], 0, v[6:7]
	v_lshl_add_u64 v[104:105], s[12:13], 0, v[10:11]
	v_lshl_add_u64 v[106:107], s[36:37], 0, v[14:15]
	s_mov_b64 s[14:15], 0
	v_mov_b32_e32 v1, v0
	v_mov_b32_e32 v2, v0
	v_lshl_add_u64 v[248:249], v[106:107], 0, s[14:15]
	v_add_co_u32_e32 v250, vcc, 0xe81d000, v248
	v_lshl_add_u64 v[238:239], v[98:99], 0, s[14:15]
	s_nop 0
	v_addc_co_u32_e32 v251, vcc, 0, v249, vcc
	v_add_co_u32_e32 v252, vcc, 0xe82d000, v248
	v_lshl_add_u64 v[240:241], v[100:101], 0, s[14:15]
	s_nop 0
	v_addc_co_u32_e32 v253, vcc, 0, v249, vcc
	v_add_co_u32_e32 v112, vcc, 0xe83d000, v248
	global_load_dwordx4 v[222:225], v[238:239], off
	global_load_dwordx4 v[226:229], v[240:241], off
	v_addc_co_u32_e32 v113, vcc, 0, v249, vcc
	v_lshl_add_u64 v[238:239], v[102:103], 0, s[14:15]
	v_lshl_add_u64 v[240:241], v[104:105], 0, s[14:15]
	v_add_co_u32_e32 v114, vcc, 0xe84d000, v248
	global_load_dwordx4 v[230:233], v[238:239], off
	global_load_dwordx4 v[234:237], v[240:241], off
	s_nop 0
	global_load_dwordx4 v[238:241], v[250:251], off offset:128
	global_load_dwordx4 v[242:245], v[252:253], off offset:128
	v_addc_co_u32_e32 v115, vcc, 0, v249, vcc
	global_load_dwordx4 v[248:251], v[112:113], off offset:128
	global_load_dwordx4 v[252:255], v[114:115], off offset:128
	s_waitcnt vmcnt(15)
	ds_write_b128 v108, v[72:75] offset:36864
	s_waitcnt vmcnt(14)
	ds_write_b128 v108, v[84:87] offset:41472
	s_waitcnt vmcnt(13)
	ds_write_b128 v108, v[88:91] offset:46080
	s_waitcnt vmcnt(12)
	ds_write_b128 v108, v[92:95] offset:50688
	s_waitcnt vmcnt(11)
	ds_write_b128 v108, v[64:67]
	s_waitcnt vmcnt(10)
	ds_write_b128 v108, v[68:71] offset:4608
	s_waitcnt vmcnt(9)
	ds_write_b128 v108, v[76:79] offset:9216
	s_waitcnt vmcnt(8)
	ds_write_b128 v108, v[80:83] offset:13824
	s_waitcnt lgkmcnt(0)
	s_barrier
; __device__ __forceinline__ f32x16 mfma32(bf16x8 a, bf16x8 b, f32x16 c) { return __builtin_amdgcn_mfma_f32_32x32x16_bf16(a, b, c, 0, 0, 0); }
; template <class ARowF, class KOffF>
; __device__ __forceinline__ void gemm_kloop(f32x16 (&acc)[2][2], ARowF arow, KOffF koff, const u16* __restrict__ Bt, int m0, int n0, unsigned char* smem) {
;     ...
;   for (int kt = 0; kt < 16; ++kt) {
;     const int buf = kt & 1;
;     if (kt + 1 < 16) {
;       const size_t ko = koff((kt + 1) * 64); const int kb = (kt + 1) * 64;
;       ra0 = *(const u32x4*)(pa0 + ko); ra1 = *(const u32x4*)(pa1 + ko); ra2 = *(const u32x4*)(pa2 + ko); ra3 = *(const u32x4*)(pa3 + ko);
;       rb0 = *(const u32x4*)(pb0 + kb); rb1 = *(const u32x4*)(pb0 + 32 * 1024 + kb); rb2 = *(const u32x4*)(pb0 + 64 * 1024 + kb); rb3 = *(const u32x4*)(pb0 + 96 * 1024 + kb);
;     }
;     const u16* cA = sA + buf * 128 * 72 + (wm * 64 + l31) * 72 + hf * 8;
;     const u16* cB = sB + buf * 128 * 72 + (wn * 64 + l31) * 72 + hf * 8;
; #pragma unroll
;     for (int ks = 0; ks < 4; ++ks) {
;       bf16x8 a0 = *(const bf16x8*)(cA + ks * 16);
;       bf16x8 a1 = *(const bf16x8*)(cA + 32 * 72 + ks * 16);
;       bf16x8 b0 = *(const bf16x8*)(cB + ks * 16);
;       bf16x8 b1 = *(const bf16x8*)(cB + 32 * 72 + ks * 16);
;       acc[0][0] = mfma32(a0, b0, acc[0][0]);
;       acc[0][1] = mfma32(a0, b1, acc[0][1]);
;       acc[1][0] = mfma32(a1, b0, acc[1][0]);
;       acc[1][1] = mfma32(a1, b1, acc[1][1]);
	v_mov_b32_e32 v3, v0
	v_mov_b32_e32 v4, v0
	v_mov_b32_e32 v5, v0
	v_mov_b32_e32 v6, v0
	v_mov_b32_e32 v7, v0
	v_mov_b32_e32 v8, v0
	v_mov_b32_e32 v9, v0
	v_mov_b32_e32 v10, v0
	v_mov_b32_e32 v11, v0
	v_mov_b32_e32 v12, v0
	v_mov_b32_e32 v13, v0
	v_mov_b32_e32 v14, v0
	v_mov_b32_e32 v15, v0
	v_mov_b32_e32 v16, v0
	v_mov_b32_e32 v17, v0
	v_mov_b32_e32 v18, v0
	v_mov_b32_e32 v19, v0
	v_mov_b32_e32 v20, v0
	v_mov_b32_e32 v21, v0
	v_mov_b32_e32 v22, v0
	v_mov_b32_e32 v23, v0
	v_mov_b32_e32 v24, v0
	v_mov_b32_e32 v25, v0
	v_mov_b32_e32 v26, v0
	v_mov_b32_e32 v27, v0
	v_mov_b32_e32 v28, v0
	v_mov_b32_e32 v29, v0
	v_mov_b32_e32 v30, v0
	v_mov_b32_e32 v31, v0
	v_mov_b32_e32 v32, v0
	v_mov_b32_e32 v33, v0
	v_mov_b32_e32 v34, v0
	v_mov_b32_e32 v35, v0
	v_mov_b32_e32 v36, v0
	v_mov_b32_e32 v37, v0
	v_mov_b32_e32 v38, v0
	v_mov_b32_e32 v39, v0
	v_mov_b32_e32 v40, v0
	v_mov_b32_e32 v41, v0
	v_mov_b32_e32 v42, v0
	v_mov_b32_e32 v43, v0
	v_mov_b32_e32 v44, v0
	v_mov_b32_e32 v45, v0
	v_mov_b32_e32 v46, v0
	v_mov_b32_e32 v47, v0
	v_mov_b32_e32 v48, v0
	v_mov_b32_e32 v49, v0
	v_mov_b32_e32 v50, v0
	v_mov_b32_e32 v51, v0
	v_mov_b32_e32 v52, v0
	v_mov_b32_e32 v53, v0
	v_mov_b32_e32 v54, v0
	v_mov_b32_e32 v55, v0
	v_mov_b32_e32 v56, v0
	v_mov_b32_e32 v57, v0
	v_mov_b32_e32 v58, v0
	v_mov_b32_e32 v59, v0
	v_mov_b32_e32 v60, v0
	v_mov_b32_e32 v61, v0
	v_mov_b32_e32 v62, v0
	v_mov_b32_e32 v63, v0
	s_branch .LBB0_399
.LBB0_399:
.Lgemm_p5a_loop:
	v_lshl_add_u64 v[88:89], v[106:107], 0, s[14:15]
	v_add_co_u32_e32 v90, vcc, 0xe81d000, v88
	v_lshl_add_u64 v[72:73], v[98:99], 0, s[14:15]
	s_nop 0
	v_addc_co_u32_e32 v91, vcc, 0, v89, vcc
	v_add_co_u32_e32 v92, vcc, 0xe82d000, v88
	v_lshl_add_u64 v[74:75], v[100:101], 0, s[14:15]
	s_nop 0
	v_addc_co_u32_e32 v93, vcc, 0, v89, vcc
	v_add_co_u32_e32 v112, vcc, 0xe83d000, v88
	global_load_dwordx4 v[64:67], v[72:73], off offset:128
	global_load_dwordx4 v[68:71], v[74:75], off offset:128
	v_addc_co_u32_e32 v113, vcc, 0, v89, vcc
	v_lshl_add_u64 v[72:73], v[102:103], 0, s[14:15]
	v_lshl_add_u64 v[74:75], v[104:105], 0, s[14:15]
	v_add_co_u32_e32 v114, vcc, 0xe84d000, v88
	global_load_dwordx4 v[76:79], v[72:73], off offset:128
	global_load_dwordx4 v[80:83], v[74:75], off offset:128
	s_nop 0
	global_load_dwordx4 v[72:75], v[90:91], off offset:256
	global_load_dwordx4 v[84:87], v[92:93], off offset:256
	v_addc_co_u32_e32 v115, vcc, 0, v89, vcc
	global_load_dwordx4 v[88:91], v[112:113], off offset:256
	global_load_dwordx4 v[92:95], v[114:115], off offset:256
	ds_read_b128 v[112:115], v110
	ds_read_b128 v[116:119], v109 offset:36864
	ds_read_b128 v[120:123], v110 offset:32
	ds_read_b128 v[124:127], v109 offset:36896
	ds_read_b128 v[128:131], v109 offset:41472
	ds_read_b128 v[132:135], v109 offset:41504
	s_waitcnt lgkmcnt(4)
	v_mfma_f32_32x32x16_bf16 v[48:63], v[112:115], v[116:119], v[48:63]
	s_waitcnt lgkmcnt(1)
	v_mfma_f32_32x32x16_bf16 v[32:47], v[112:115], v[128:131], v[32:47]
	ds_read_b128 v[112:115], v110 offset:4608
	ds_read_b128 v[136:139], v110 offset:4640
	s_waitcnt lgkmcnt(1)
	v_mfma_f32_32x32x16_bf16 v[16:31], v[112:115], v[116:119], v[16:31]
	v_mfma_f32_32x32x16_bf16 v[0:15], v[112:115], v[128:131], v[0:15]
	v_mfma_f32_32x32x16_bf16 v[48:63], v[120:123], v[124:127], v[48:63]
	v_mfma_f32_32x32x16_bf16 v[32:47], v[120:123], v[132:135], v[32:47]
	s_waitcnt lgkmcnt(0)
	v_mfma_f32_32x32x16_bf16 v[16:31], v[136:139], v[124:127], v[16:31]
	ds_read_b128 v[112:115], v110 offset:64
	ds_read_b128 v[116:119], v109 offset:36928
	ds_read_b128 v[120:123], v110 offset:96
	ds_read_b128 v[124:127], v109 offset:36960
	v_mfma_f32_32x32x16_bf16 v[0:15], v[136:139], v[132:135], v[0:15]
	ds_read_b128 v[128:131], v109 offset:41536
	ds_read_b128 v[132:135], v109 offset:41568
	s_waitcnt lgkmcnt(4)
	v_mfma_f32_32x32x16_bf16 v[48:63], v[112:115], v[116:119], v[48:63]
	s_waitcnt lgkmcnt(1)
	v_mfma_f32_32x32x16_bf16 v[32:47], v[112:115], v[128:131], v[32:47]
	ds_read_b128 v[112:115], v110 offset:4672
	ds_read_b128 v[136:139], v110 offset:4704
	s_waitcnt lgkmcnt(1)
	v_mfma_f32_32x32x16_bf16 v[16:31], v[112:115], v[116:119], v[16:31]
	v_mfma_f32_32x32x16_bf16 v[0:15], v[112:115], v[128:131], v[0:15]
	v_mfma_f32_32x32x16_bf16 v[48:63], v[120:123], v[124:127], v[48:63]
	v_mfma_f32_32x32x16_bf16 v[32:47], v[120:123], v[132:135], v[32:47]
	s_waitcnt lgkmcnt(0)
	v_mfma_f32_32x32x16_bf16 v[16:31], v[136:139], v[124:127], v[16:31]
	v_mfma_f32_32x32x16_bf16 v[0:15], v[136:139], v[132:135], v[0:15]
	v_add_u32_e32 v96, 18432, v108
	s_waitcnt vmcnt(15)
	ds_write_b128 v96, v[222:225]
	s_waitcnt vmcnt(14)
	ds_write_b128 v96, v[226:229] offset:4608
	s_waitcnt vmcnt(13)
	ds_write_b128 v96, v[230:233] offset:9216
	s_waitcnt vmcnt(12)
	ds_write_b128 v96, v[234:237] offset:13824
	s_waitcnt vmcnt(11)
	ds_write_b128 v96, v[238:241] offset:36864
	s_waitcnt vmcnt(10)
	ds_write_b128 v96, v[242:245] offset:41472
	s_waitcnt vmcnt(9)
	ds_write_b128 v96, v[248:251] offset:46080
	s_waitcnt vmcnt(8)
	ds_write_b128 v96, v[252:255] offset:50688
	s_waitcnt lgkmcnt(0)
	s_barrier
; __device__ __forceinline__ f32x16 mfma32(bf16x8 a, bf16x8 b, f32x16 c) { return __builtin_amdgcn_mfma_f32_32x32x16_bf16(a, b, c, 0, 0, 0); }
; template <class ARowF, class KOffF>
; __device__ __forceinline__ void gemm_kloop(f32x16 (&acc)[2][2], ARowF arow, KOffF koff, const u16* __restrict__ Bt, int m0, int n0, unsigned char* smem) {
;     ...
;     if (kt + 1 < 16) {
;       const size_t ko = koff((kt + 1) * 64); const int kb = (kt + 1) * 64;
;       ra0 = *(const u32x4*)(pa0 + ko); ra1 = *(const u32x4*)(pa1 + ko); ra2 = *(const u32x4*)(pa2 + ko); ra3 = *(const u32x4*)(pa3 + ko);
;       rb0 = *(const u32x4*)(pb0 + kb); rb1 = *(const u32x4*)(pb0 + 32 * 1024 + kb); rb2 = *(const u32x4*)(pb0 + 64 * 1024 + kb); rb3 = *(const u32x4*)(pb0 + 96 * 1024 + kb);
;     }
;     const u16* cA = sA + buf * 128 * 72 + (wm * 64 + l31) * 72 + hf * 8;
;     const u16* cB = sB + buf * 128 * 72 + (wn * 64 + l31) * 72 + hf * 8;
; #pragma unroll
;     for (int ks = 0; ks < 4; ++ks) {
;       bf16x8 a0 = *(const bf16x8*)(cA + ks * 16);
;       bf16x8 a1 = *(const bf16x8*)(cA + 32 * 72 + ks * 16);
;       bf16x8 b0 = *(const bf16x8*)(cB + ks * 16);
;       bf16x8 b1 = *(const bf16x8*)(cB + 32 * 72 + ks * 16);
;       acc[0][0] = mfma32(a0, b0, acc[0][0]);
;       acc[0][1] = mfma32(a0, b1, acc[0][1]);
;       acc[1][0] = mfma32(a1, b0, acc[1][0]);
;       acc[1][1] = mfma32(a1, b1, acc[1][1]);
;     }
;     if (kt + 1 < 16) {
;       u16* wA = wA0 + (buf ^ 1) * 128 * 72; u16* wB = wB0 + (buf ^ 1) * 128 * 72;
;       *(u32x4*)(wA) = ra0; *(u32x4*)(wA + 32 * 72) = ra1; *(u32x4*)(wA + 64 * 72) = ra2; *(u32x4*)(wA + 96 * 72) = ra3;
;       *(u32x4*)(wB) = rb0; *(u32x4*)(wB + 32 * 72) = rb1; *(u32x4*)(wB + 64 * 72) = rb2; *(u32x4*)(wB + 96 * 72) = rb3;
	v_lshl_add_u64 v[248:249], v[106:107], 0, s[14:15]
	v_add_co_u32_e32 v250, vcc, 0xe81d000, v248
	v_lshl_add_u64 v[238:239], v[98:99], 0, s[14:15]
	s_nop 0
	v_addc_co_u32_e32 v251, vcc, 0, v249, vcc
	v_add_co_u32_e32 v252, vcc, 0xe82d000, v248
	v_lshl_add_u64 v[240:241], v[100:101], 0, s[14:15]
	s_nop 0
	v_addc_co_u32_e32 v253, vcc, 0, v249, vcc
	v_add_co_u32_e32 v112, vcc, 0xe83d000, v248
	global_load_dwordx4 v[222:225], v[238:239], off offset:256
	global_load_dwordx4 v[226:229], v[240:241], off offset:256
	v_addc_co_u32_e32 v113, vcc, 0, v249, vcc
	v_lshl_add_u64 v[238:239], v[102:103], 0, s[14:15]
	v_lshl_add_u64 v[240:241], v[104:105], 0, s[14:15]
	v_add_co_u32_e32 v114, vcc, 0xe84d000, v248
	global_load_dwordx4 v[230:233], v[238:239], off offset:256
	global_load_dwordx4 v[234:237], v[240:241], off offset:256
	s_nop 0
	global_load_dwordx4 v[238:241], v[250:251], off offset:384
	global_load_dwordx4 v[242:245], v[252:253], off offset:384
	v_addc_co_u32_e32 v115, vcc, 0, v249, vcc
	global_load_dwordx4 v[248:251], v[112:113], off offset:384
	global_load_dwordx4 v[252:255], v[114:115], off offset:384
	ds_read_b128 v[112:115], v110 offset:18432
	ds_read_b128 v[116:119], v109 offset:55296
	ds_read_b128 v[120:123], v110 offset:18464
	ds_read_b128 v[124:127], v109 offset:55328
	ds_read_b128 v[128:131], v109 offset:59904
	ds_read_b128 v[132:135], v109 offset:59936
	s_waitcnt lgkmcnt(4)
	v_mfma_f32_32x32x16_bf16 v[48:63], v[112:115], v[116:119], v[48:63]
	s_waitcnt lgkmcnt(1)
	v_mfma_f32_32x32x16_bf16 v[32:47], v[112:115], v[128:131], v[32:47]
	ds_read_b128 v[112:115], v110 offset:23040
	ds_read_b128 v[136:139], v110 offset:23072
	s_waitcnt lgkmcnt(1)
	v_mfma_f32_32x32x16_bf16 v[16:31], v[112:115], v[116:119], v[16:31]
	v_mfma_f32_32x32x16_bf16 v[0:15], v[112:115], v[128:131], v[0:15]
	v_mfma_f32_32x32x16_bf16 v[48:63], v[120:123], v[124:127], v[48:63]
	v_mfma_f32_32x32x16_bf16 v[32:47], v[120:123], v[132:135], v[32:47]
	s_waitcnt lgkmcnt(0)
	v_mfma_f32_32x32x16_bf16 v[16:31], v[136:139], v[124:127], v[16:31]
	ds_read_b128 v[112:115], v110 offset:18496
	ds_read_b128 v[116:119], v109 offset:55360
	ds_read_b128 v[120:123], v110 offset:18528
	ds_read_b128 v[124:127], v109 offset:55392
	v_mfma_f32_32x32x16_bf16 v[0:15], v[136:139], v[132:135], v[0:15]
	ds_read_b128 v[128:131], v109 offset:59968
	ds_read_b128 v[132:135], v109 offset:60000
	s_waitcnt lgkmcnt(4)
	v_mfma_f32_32x32x16_bf16 v[48:63], v[112:115], v[116:119], v[48:63]
	s_waitcnt lgkmcnt(1)
	v_mfma_f32_32x32x16_bf16 v[32:47], v[112:115], v[128:131], v[32:47]
	ds_read_b128 v[112:115], v110 offset:23104
	ds_read_b128 v[136:139], v110 offset:23136
	s_waitcnt lgkmcnt(1)
	v_mfma_f32_32x32x16_bf16 v[16:31], v[112:115], v[116:119], v[16:31]
	v_mfma_f32_32x32x16_bf16 v[0:15], v[112:115], v[128:131], v[0:15]
	v_mfma_f32_32x32x16_bf16 v[48:63], v[120:123], v[124:127], v[48:63]
	v_mfma_f32_32x32x16_bf16 v[32:47], v[120:123], v[132:135], v[32:47]
	s_waitcnt lgkmcnt(0)
	v_mfma_f32_32x32x16_bf16 v[16:31], v[136:139], v[124:127], v[16:31]
	v_mfma_f32_32x32x16_bf16 v[0:15], v[136:139], v[132:135], v[0:15]
	v_mov_b32_e32 v96, v108
	s_waitcnt vmcnt(15)
	ds_write_b128 v96, v[64:67]
	s_waitcnt vmcnt(14)
	ds_write_b128 v96, v[68:71] offset:4608
	s_waitcnt vmcnt(13)
	ds_write_b128 v96, v[76:79] offset:9216
	s_waitcnt vmcnt(12)
	ds_write_b128 v96, v[80:83] offset:13824
	s_waitcnt vmcnt(11)
	ds_write_b128 v96, v[72:75] offset:36864
	s_waitcnt vmcnt(10)
	ds_write_b128 v96, v[84:87] offset:41472
	s_waitcnt vmcnt(9)
	ds_write_b128 v96, v[88:91] offset:46080
	s_waitcnt vmcnt(8)
	ds_write_b128 v96, v[92:95] offset:50688
	s_waitcnt lgkmcnt(0)
	s_barrier
	s_add_u32 s14, s14, 0x100
	s_addc_u32 s15, s15, 0
	s_cmpk_lg_i32 s14, 0x700
	s_cbranch_scc1 .Lgemm_p5a_loop
; __device__ __forceinline__ f32x16 mfma32(bf16x8 a, bf16x8 b, f32x16 c) { return __builtin_amdgcn_mfma_f32_32x32x16_bf16(a, b, c, 0, 0, 0); }
; __device__ __forceinline__ void lds_barrier() { asm volatile("s_waitcnt lgkmcnt(0)\n\ts_barrier" ::: "memory"); }
; template <class ARowF, class KOffF>
; __device__ __forceinline__ void gemm_kloop(f32x16 (&acc)[2][2], ARowF arow, KOffF koff, const u16* __restrict__ Bt, int m0, int n0, unsigned char* smem) {
;     ...
;   for (int kt = 0; kt < 16; ++kt) {
;     const int buf = kt & 1;
;     if (kt + 1 < 16) {
;       const size_t ko = koff((kt + 1) * 64); const int kb = (kt + 1) * 64;
;       ra0 = *(const u32x4*)(pa0 + ko); ra1 = *(const u32x4*)(pa1 + ko); ra2 = *(const u32x4*)(pa2 + ko); ra3 = *(const u32x4*)(pa3 + ko);
;       rb0 = *(const u32x4*)(pb0 + kb); rb1 = *(const u32x4*)(pb0 + 32 * 1024 + kb); rb2 = *(const u32x4*)(pb0 + 64 * 1024 + kb); rb3 = *(const u32x4*)(pb0 + 96 * 1024 + kb);
;     }
;     const u16* cA = sA + buf * 128 * 72 + (wm * 64 + l31) * 72 + hf * 8;
;     const u16* cB = sB + buf * 128 * 72 + (wn * 64 + l31) * 72 + hf * 8;
; #pragma unroll
;     for (int ks = 0; ks < 4; ++ks) {
;       bf16x8 a0 = *(const bf16x8*)(cA + ks * 16);
;       bf16x8 a1 = *(const bf16x8*)(cA + 32 * 72 + ks * 16);
;       bf16x8 b0 = *(const bf16x8*)(cB + ks * 16);
;       bf16x8 b1 = *(const bf16x8*)(cB + 32 * 72 + ks * 16);
;       acc[0][0] = mfma32(a0, b0, acc[0][0]);
;       acc[0][1] = mfma32(a0, b1, acc[0][1]);
;       acc[1][0] = mfma32(a1, b0, acc[1][0]);
;       acc[1][1] = mfma32(a1, b1, acc[1][1]);
;     }
;     if (kt + 1 < 16) {
;       u16* wA = wA0 + (buf ^ 1) * 128 * 72; u16* wB = wB0 + (buf ^ 1) * 128 * 72;
;       *(u32x4*)(wA) = ra0; *(u32x4*)(wA + 32 * 72) = ra1; *(u32x4*)(wA + 64 * 72) = ra2; *(u32x4*)(wA + 96 * 72) = ra3;
;       *(u32x4*)(wB) = rb0; *(u32x4*)(wB + 32 * 72) = rb1; *(u32x4*)(wB + 64 * 72) = rb2; *(u32x4*)(wB + 96 * 72) = rb3;
;     }
;     lds_barrier();
;   }
	ds_read_b128 v[112:115], v110
	ds_read_b128 v[116:119], v109 offset:36864
	ds_read_b128 v[120:123], v110 offset:32
	ds_read_b128 v[124:127], v109 offset:36896
	ds_read_b128 v[128:131], v109 offset:41472
	ds_read_b128 v[132:135], v109 offset:41504
	s_waitcnt lgkmcnt(4)
	v_mfma_f32_32x32x16_bf16 v[48:63], v[112:115], v[116:119], v[48:63]
	s_waitcnt lgkmcnt(1)
	v_mfma_f32_32x32x16_bf16 v[32:47], v[112:115], v[128:131], v[32:47]
	ds_read_b128 v[112:115], v110 offset:4608
	ds_read_b128 v[136:139], v110 offset:4640
	s_waitcnt lgkmcnt(1)
	v_mfma_f32_32x32x16_bf16 v[16:31], v[112:115], v[116:119], v[16:31]
	v_mfma_f32_32x32x16_bf16 v[0:15], v[112:115], v[128:131], v[0:15]
	v_mfma_f32_32x32x16_bf16 v[48:63], v[120:123], v[124:127], v[48:63]
	v_mfma_f32_32x32x16_bf16 v[32:47], v[120:123], v[132:135], v[32:47]
	s_waitcnt lgkmcnt(0)
	v_mfma_f32_32x32x16_bf16 v[16:31], v[136:139], v[124:127], v[16:31]
	ds_read_b128 v[112:115], v110 offset:64
	ds_read_b128 v[116:119], v109 offset:36928
	ds_read_b128 v[120:123], v110 offset:96
	ds_read_b128 v[124:127], v109 offset:36960
	v_mfma_f32_32x32x16_bf16 v[0:15], v[136:139], v[132:135], v[0:15]
	ds_read_b128 v[128:131], v109 offset:41536
	ds_read_b128 v[132:135], v109 offset:41568
	s_waitcnt lgkmcnt(4)
	v_mfma_f32_32x32x16_bf16 v[48:63], v[112:115], v[116:119], v[48:63]
	s_waitcnt lgkmcnt(1)
	v_mfma_f32_32x32x16_bf16 v[32:47], v[112:115], v[128:131], v[32:47]
	ds_read_b128 v[112:115], v110 offset:4672
	ds_read_b128 v[136:139], v110 offset:4704
	s_waitcnt lgkmcnt(1)
	v_mfma_f32_32x32x16_bf16 v[16:31], v[112:115], v[116:119], v[16:31]
	v_mfma_f32_32x32x16_bf16 v[0:15], v[112:115], v[128:131], v[0:15]
	v_mfma_f32_32x32x16_bf16 v[48:63], v[120:123], v[124:127], v[48:63]
	v_mfma_f32_32x32x16_bf16 v[32:47], v[120:123], v[132:135], v[32:47]
	s_waitcnt lgkmcnt(0)
	v_mfma_f32_32x32x16_bf16 v[16:31], v[136:139], v[124:127], v[16:31]
	v_mfma_f32_32x32x16_bf16 v[0:15], v[136:139], v[132:135], v[0:15]
	v_add_u32_e32 v96, 18432, v108
	s_waitcnt vmcnt(7)
	ds_write_b128 v96, v[222:225]
	s_waitcnt vmcnt(6)
	ds_write_b128 v96, v[226:229] offset:4608
	s_waitcnt vmcnt(5)
	ds_write_b128 v96, v[230:233] offset:9216
	s_waitcnt vmcnt(4)
	ds_write_b128 v96, v[234:237] offset:13824
	s_waitcnt vmcnt(3)
	ds_write_b128 v96, v[238:241] offset:36864
	s_waitcnt vmcnt(2)
	ds_write_b128 v96, v[242:245] offset:41472
	s_waitcnt vmcnt(1)
	ds_write_b128 v96, v[248:251] offset:46080
	s_waitcnt vmcnt(0)
	ds_write_b128 v96, v[252:255] offset:50688
	s_waitcnt lgkmcnt(0)
	s_barrier
	ds_read_b128 v[112:115], v110 offset:18432
	ds_read_b128 v[116:119], v109 offset:55296
	ds_read_b128 v[120:123], v110 offset:18464
	ds_read_b128 v[124:127], v109 offset:55328
	ds_read_b128 v[128:131], v109 offset:59904
	ds_read_b128 v[132:135], v109 offset:59936
	s_waitcnt lgkmcnt(4)
	v_mfma_f32_32x32x16_bf16 v[48:63], v[112:115], v[116:119], v[48:63]
	s_waitcnt lgkmcnt(1)
	v_mfma_f32_32x32x16_bf16 v[32:47], v[112:115], v[128:131], v[32:47]
	ds_read_b128 v[112:115], v110 offset:23040
	ds_read_b128 v[136:139], v110 offset:23072
	s_waitcnt lgkmcnt(1)
	v_mfma_f32_32x32x16_bf16 v[16:31], v[112:115], v[116:119], v[16:31]
	v_mfma_f32_32x32x16_bf16 v[0:15], v[112:115], v[128:131], v[0:15]
	v_mfma_f32_32x32x16_bf16 v[48:63], v[120:123], v[124:127], v[48:63]
	v_mfma_f32_32x32x16_bf16 v[32:47], v[120:123], v[132:135], v[32:47]
	s_waitcnt lgkmcnt(0)
	v_mfma_f32_32x32x16_bf16 v[16:31], v[136:139], v[124:127], v[16:31]
	ds_read_b128 v[112:115], v110 offset:18496
	ds_read_b128 v[116:119], v109 offset:55360
	ds_read_b128 v[120:123], v110 offset:18528
	ds_read_b128 v[124:127], v109 offset:55392
	v_mfma_f32_32x32x16_bf16 v[0:15], v[136:139], v[132:135], v[0:15]
	ds_read_b128 v[128:131], v109 offset:59968
	ds_read_b128 v[132:135], v109 offset:60000
	s_waitcnt lgkmcnt(4)
	v_mfma_f32_32x32x16_bf16 v[48:63], v[112:115], v[116:119], v[48:63]
	s_waitcnt lgkmcnt(1)
	v_mfma_f32_32x32x16_bf16 v[32:47], v[112:115], v[128:131], v[32:47]
	ds_read_b128 v[112:115], v110 offset:23104
	ds_read_b128 v[136:139], v110 offset:23136
	s_waitcnt lgkmcnt(1)
	v_mfma_f32_32x32x16_bf16 v[16:31], v[112:115], v[116:119], v[16:31]
	v_mfma_f32_32x32x16_bf16 v[0:15], v[112:115], v[128:131], v[0:15]
	v_mfma_f32_32x32x16_bf16 v[48:63], v[120:123], v[124:127], v[48:63]
	v_mfma_f32_32x32x16_bf16 v[32:47], v[120:123], v[132:135], v[32:47]
	s_waitcnt lgkmcnt(0)
	v_mfma_f32_32x32x16_bf16 v[16:31], v[136:139], v[124:127], v[16:31]
	v_mfma_f32_32x32x16_bf16 v[0:15], v[136:139], v[132:135], v[0:15]
	s_waitcnt lgkmcnt(0)
	s_barrier
	s_nop 5

; __device__ __forceinline__ bool tile_map(int i, int xcd, int MT, int NT, int& mt, int& nt) {
;   int cm = (MT - xcd + 7) >> 3;
;   int ag = i / (8 * NT);
;   if (ag * 8 >= cm) return false;
;   int gs = cm - ag * 8; if (gs > 8) gs = 8;
;   int j = i - ag * 8 * NT;
;   if (j >= gs * NT) return false;
;   int al = j % gs; nt = j / gs;
;   mt = xcd + 8 * (8 * ag + al);
;   return true;
; __device__ __forceinline__ void phase5(const Params& p, unsigned char* smem) {
;     ...
;     gemm_kloop(acc, [&](int m) {
;       int bb = m >> 13, t = m & 8191; int pp = t + 64;
;       return DX + (((size_t)((bb * 8) * NCH + (pp >> 6))) * 3) * 8192 + (pp & 63) * 128;
;     }, [](int k0) { return (size_t)(k0 >> 7) * ((size_t)NCH * 3 * 8192) + (size_t)(k0 & 127); }, wdt, m0, n0, smem);
.LBB0_408:
	s_sub_i32 s14, 16, s18
	s_min_u32 s14, s14, 8
	s_lshl_b32 s16, s18, 3
	s_sub_i32 s19, s28, s16
	s_lshl_b32 s16, s14, 3
	s_cmp_ge_i32 s19, s16
	s_mov_b64 s[16:17], -1
	s_cbranch_scc1 .LBB0_407
	v_cvt_f32_u32_e32 v0, s14
	s_sub_i32 s29, 0, s14
	s_abs_i32 s17, s19
	s_ashr_i32 s16, s19, 31
	v_rcp_iflag_f32_e32 v0, v0
	v_mov_b32_e32 v8, v218
	v_mov_b32_e32 v5, v97
	v_mul_f32_e32 v0, 0x4f7ffffe, v0
	v_cvt_u32_f32_e32 v0, v0
	v_ashrrev_i32_e32 v9, 3, v8
	v_lshlrev_b32_e32 v4, 8, v9
	v_and_b32_e32 v96, 0x3f00, v4
	v_readfirstlane_b32 s30, v0
	s_mul_i32 s29, s29, s30
	s_mul_hi_u32 s29, s30, s29
	s_add_i32 s30, s30, s29
	s_mul_hi_u32 s29, s17, s30
	s_mul_i32 s30, s29, s14
	s_sub_i32 s17, s17, s30
	s_add_i32 s31, s29, 1
	s_sub_i32 s30, s17, s14
	s_cmp_ge_u32 s17, s14
	s_cselect_b32 s29, s31, s29
	s_cselect_b32 s17, s30, s17
	s_add_i32 s30, s29, 1
	s_cmp_ge_u32 s17, s14
	s_cselect_b32 s17, s30, s29
	s_xor_b32 s17, s17, s16
	s_sub_i32 s16, s17, s16
	s_mul_i32 s14, s16, s14
	s_sub_i32 s14, s19, s14
	s_add_i32 s14, s14, s18
	s_lshl_b32 s14, s14, 10
	s_or_b32 s29, s14, s2
	v_add_u32_e32 v10, s29, v9
	v_and_b32_e32 v0, 0x1fc0, v10
	v_add_u32_e32 v0, 64, v0
	v_ashrrev_i32_e32 v1, 10, v10
	v_and_b32_e32 v1, 0xfffff8, v1
	v_lshrrev_b32_e32 v0, 6, v0
	v_mad_i32_i24 v2, v1, s20, v0
	v_mov_b64_e32 v[0:1], s[8:9]
	s_lshl_b32 s30, s16, 7
	v_mad_i64_i32 v[2:3], s[16:17], v2, s21, v[0:1]
	v_lshlrev_b32_e32 v4, 4, v8
	v_lshl_add_u64 v[2:3], v[2:3], 0, v[96:97]
	v_and_b32_e32 v4, 0x70, v4
	v_add_u32_e32 v6, 32, v10
	v_lshl_add_u64 v[98:99], v[2:3], 0, v[4:5]
	v_and_b32_e32 v2, 0x1fc0, v6
	v_add_u32_e32 v2, 64, v2
	v_ashrrev_i32_e32 v3, 10, v6
	v_and_b32_e32 v3, 0xfffff8, v3
	v_lshrrev_b32_e32 v2, 6, v2
	v_mad_i32_i24 v2, v3, s20, v2
	v_lshlrev_b32_e32 v6, 8, v6
	v_mad_i64_i32 v[2:3], s[16:17], v2, s21, v[0:1]
	v_and_b32_e32 v6, 0x3f00, v6
	v_mov_b32_e32 v7, v97
	v_lshl_add_u64 v[2:3], v[2:3], 0, v[6:7]
	v_lshl_add_u64 v[100:101], v[2:3], 0, v[4:5]
	v_add_u32_e32 v2, 64, v10
	v_and_b32_e32 v3, 0x1fc0, v2
	v_add_u32_e32 v3, 64, v3
	v_ashrrev_i32_e32 v2, 10, v2
	v_and_b32_e32 v2, 0xfffff8, v2
	v_lshrrev_b32_e32 v3, 6, v3
	v_mad_i32_i24 v2, v2, s20, v3
	v_mad_i64_i32 v[2:3], s[16:17], v2, s21, v[0:1]
	v_lshl_add_u64 v[2:3], v[2:3], 0, v[96:97]
	v_lshl_add_u64 v[102:103], v[2:3], 0, v[4:5]
	v_add_u32_e32 v2, 0x60, v10
	v_and_b32_e32 v3, 0x1fc0, v2
	v_add_u32_e32 v3, 64, v3
	v_ashrrev_i32_e32 v6, 10, v2
	v_and_b32_e32 v6, 0xfffff8, v6
	v_lshrrev_b32_e32 v3, 6, v3
	v_mad_i32_i24 v3, v6, s20, v3
	v_lshlrev_b32_e32 v2, 8, v2
	v_mad_i64_i32 v[0:1], s[16:17], v3, s21, v[0:1]
	v_and_b32_e32 v96, 0x3f00, v2
	v_lshl_add_u64 v[0:1], v[0:1], 0, v[96:97]
	v_lshl_add_u64 v[104:105], v[0:1], 0, v[4:5]
	v_add_u32_e32 v0, s30, v9
	v_ashrrev_i32_e32 v1, 31, v0
	v_lshlrev_b64 v[0:1], 11, v[0:1]
	v_lshl_add_u64 v[2:3], s[12:13], 0, v[0:1]
	v_lshl_add_u64 v[2:3], v[2:3], 0, v[4:5]
	v_add_co_u32_e32 v6, vcc, s22, v2
	global_load_dwordx4 v[64:67], v[98:99], off
	global_load_dwordx4 v[68:71], v[100:101], off
	global_load_dwordx4 v[72:75], v[102:103], off
	global_load_dwordx4 v[76:79], v[104:105], off
	v_addc_co_u32_e32 v7, vcc, 0, v3, vcc
	global_load_dwordx4 v[80:83], v[2:3], off
	global_load_dwordx4 v[84:87], v[6:7], off
	v_add_co_u32_e32 v6, vcc, s23, v2
	s_mov_b32 s31, 1
	s_nop 0
	v_addc_co_u32_e32 v7, vcc, 0, v3, vcc
	v_add_co_u32_e32 v2, vcc, s24, v2
	s_mov_b32 s34, 64
	s_nop 0
	v_addc_co_u32_e32 v3, vcc, 0, v3, vcc
	global_load_dwordx4 v[88:91], v[6:7], off
	global_load_dwordx4 v[92:95], v[2:3], off
	v_mul_lo_u32 v3, v9, s25
	v_and_b32_e32 v2, 31, v8
	v_add3_u32 v96, 16, v3, v4
	v_lshrrev_b32_e32 v3, 1, v8
	v_and_or_b32 v2, v3, s26, v2
	v_mul_lo_u32 v2, v2, s25
	v_and_b32_e32 v3, 16, v3
	v_add3_u32 v108, 16, v2, v3
	v_and_b32_e32 v2, 0x5f, v8
	v_mul_u32_u24_e32 v2, 0x90, v2
	v_add3_u32 v109, 16, v2, v3
	v_and_b32_e32 v2, 7, v8
	v_lshl_or_b32 v0, v2, 4, v0
	v_lshl_add_u64 v[106:107], s[36:37], 0, v[0:1]
	v_mov_b32_e32 v0, 0
	s_mov_b64 s[16:17], 0
	v_mov_b32_e32 v1, v0
	v_mov_b32_e32 v2, v0
	v_mov_b32_e32 v3, v0
	v_mov_b32_e32 v4, v0
	v_mov_b32_e32 v5, v0
	v_mov_b32_e32 v6, v0
	v_mov_b32_e32 v7, v0
	v_mov_b32_e32 v8, v0
	v_mov_b32_e32 v9, v0
	v_mov_b32_e32 v10, v0
	v_mov_b32_e32 v11, v0
	v_mov_b32_e32 v12, v0
	v_mov_b32_e32 v13, v0
	v_mov_b32_e32 v14, v0
	v_mov_b32_e32 v15, v0
	v_mov_b32_e32 v16, v0
	v_mov_b32_e32 v17, v0
	v_mov_b32_e32 v18, v0
	v_mov_b32_e32 v19, v0
	v_mov_b32_e32 v20, v0
	v_mov_b32_e32 v21, v0
	v_mov_b32_e32 v22, v0
	v_mov_b32_e32 v23, v0
	v_mov_b32_e32 v24, v0
	s_mov_b32 s38, 0x60c000
	s_mov_b32 s39, 0
	v_lshl_add_u64 v[248:249], v[106:107], 0, s[16:17]
	v_add_co_u32_e32 v250, vcc, 0xea1d000, v248
	s_nop 1
	v_addc_co_u32_e32 v251, vcc, 0, v249, vcc
	v_add_co_u32_e32 v252, vcc, 0xea2d000, v248
	s_nop 1
	v_addc_co_u32_e32 v253, vcc, 0, v249, vcc
	v_add_co_u32_e32 v110, vcc, 0xea3d000, v248
	s_nop 1
	v_addc_co_u32_e32 v111, vcc, 0, v249, vcc
	v_add_co_u32_e32 v112, vcc, 0xea4d000, v248
	s_nop 1
	v_addc_co_u32_e32 v113, vcc, 0, v249, vcc
	global_load_dwordx4 v[222:225], v[98:99], off offset:128
	global_load_dwordx4 v[226:229], v[100:101], off offset:128
	global_load_dwordx4 v[230:233], v[102:103], off offset:128
	global_load_dwordx4 v[234:237], v[104:105], off offset:128
	global_load_dwordx4 v[238:241], v[250:251], off offset:128
	global_load_dwordx4 v[242:245], v[252:253], off offset:128
	global_load_dwordx4 v[248:251], v[110:111], off offset:128
	global_load_dwordx4 v[252:255], v[112:113], off offset:128
	s_waitcnt vmcnt(11)
	ds_write_b128 v96, v[80:83] offset:36864
	s_waitcnt vmcnt(10)
	ds_write_b128 v96, v[84:87] offset:41472
	ds_write_b128 v96, v[64:67]
	ds_write_b128 v96, v[68:71] offset:4608
	ds_write_b128 v96, v[72:75] offset:9216
	ds_write_b128 v96, v[76:79] offset:13824
	s_waitcnt vmcnt(9)
	ds_write_b128 v96, v[88:91] offset:46080
	s_waitcnt vmcnt(8)
	ds_write_b128 v96, v[92:95] offset:50688
	s_waitcnt lgkmcnt(0)
	s_barrier
	v_mov_b32_e32 v25, v0
	v_mov_b32_e32 v26, v0
	v_mov_b32_e32 v27, v0
	v_mov_b32_e32 v28, v0
	v_mov_b32_e32 v29, v0
	v_mov_b32_e32 v30, v0
	v_mov_b32_e32 v31, v0
	v_mov_b32_e32 v32, v0
	v_mov_b32_e32 v33, v0
	v_mov_b32_e32 v34, v0
	v_mov_b32_e32 v35, v0
	v_mov_b32_e32 v36, v0
	v_mov_b32_e32 v37, v0
	v_mov_b32_e32 v38, v0
	v_mov_b32_e32 v39, v0
	v_mov_b32_e32 v40, v0
	v_mov_b32_e32 v41, v0
	v_mov_b32_e32 v42, v0
	v_mov_b32_e32 v43, v0
	v_mov_b32_e32 v44, v0
	v_mov_b32_e32 v45, v0
	v_mov_b32_e32 v46, v0
	v_mov_b32_e32 v47, v0
	v_mov_b32_e32 v48, v0
	v_mov_b32_e32 v49, v0
	v_mov_b32_e32 v50, v0
	v_mov_b32_e32 v51, v0
	v_mov_b32_e32 v52, v0
	v_mov_b32_e32 v53, v0
	v_mov_b32_e32 v54, v0
	v_mov_b32_e32 v55, v0
	v_mov_b32_e32 v56, v0
	v_mov_b32_e32 v57, v0
	v_mov_b32_e32 v58, v0
	v_mov_b32_e32 v59, v0
	v_mov_b32_e32 v60, v0
	v_mov_b32_e32 v61, v0
	v_mov_b32_e32 v62, v0
	v_mov_b32_e32 v63, v0
	s_branch .LBB0_411
; __device__ __forceinline__ f32x16 mfma32(bf16x8 a, bf16x8 b, f32x16 c) { return __builtin_amdgcn_mfma_f32_32x32x16_bf16(a, b, c, 0, 0, 0); }
; template <class ARowF, class KOffF>
; __device__ __forceinline__ void gemm_kloop(f32x16 (&acc)[2][2], ARowF arow, KOffF koff, const u16* __restrict__ Bt, int m0, int n0, unsigned char* smem) {
;     ...
;   for (int kt = 0; kt < 16; ++kt) {
;     const int buf = kt & 1;
;     if (kt + 1 < 16) {
;       const size_t ko = koff((kt + 1) * 64); const int kb = (kt + 1) * 64;
;       ra0 = *(const u32x4*)(pa0 + ko); ra1 = *(const u32x4*)(pa1 + ko); ra2 = *(const u32x4*)(pa2 + ko); ra3 = *(const u32x4*)(pa3 + ko);
;       rb0 = *(const u32x4*)(pb0 + kb); rb1 = *(const u32x4*)(pb0 + 32 * 1024 + kb); rb2 = *(const u32x4*)(pb0 + 64 * 1024 + kb); rb3 = *(const u32x4*)(pb0 + 96 * 1024 + kb);
;     }
;     const u16* cA = sA + buf * 128 * 72 + (wm * 64 + l31) * 72 + hf * 8;
;     const u16* cB = sB + buf * 128 * 72 + (wn * 64 + l31) * 72 + hf * 8;
; #pragma unroll
;     for (int ks = 0; ks < 4; ++ks) {
;       bf16x8 a0 = *(const bf16x8*)(cA + ks * 16);
;       bf16x8 a1 = *(const bf16x8*)(cA + 32 * 72 + ks * 16);
;       bf16x8 b0 = *(const bf16x8*)(cB + ks * 16);
;       bf16x8 b1 = *(const bf16x8*)(cB + 32 * 72 + ks * 16);
;       acc[0][0] = mfma32(a0, b0, acc[0][0]);
;       acc[0][1] = mfma32(a0, b1, acc[0][1]);
;       acc[1][0] = mfma32(a1, b0, acc[1][0]);
;       acc[1][1] = mfma32(a1, b1, acc[1][1]);
.LBB0_411:
.Lgemm_p5b_loop:
	v_lshl_add_u64 v[88:89], v[106:107], 0, s[16:17]
	v_add_co_u32_e32 v90, vcc, 0xea1d000, v88
	s_nop 1
	v_addc_co_u32_e32 v91, vcc, 0, v89, vcc
	v_add_co_u32_e32 v92, vcc, 0xea2d000, v88
	s_nop 1
	v_addc_co_u32_e32 v93, vcc, 0, v89, vcc
	v_add_co_u32_e32 v110, vcc, 0xea3d000, v88
	s_nop 1
	v_addc_co_u32_e32 v111, vcc, 0, v89, vcc
	v_add_co_u32_e32 v112, vcc, 0xea4d000, v88
	s_nop 1
	v_addc_co_u32_e32 v113, vcc, 0, v89, vcc
	v_lshl_add_u64 v[72:73], v[98:99], 0, s[38:39]
	v_lshl_add_u64 v[74:75], v[100:101], 0, s[38:39]
	v_lshl_add_u64 v[80:81], v[102:103], 0, s[38:39]
	v_lshl_add_u64 v[82:83], v[104:105], 0, s[38:39]
	global_load_dwordx4 v[64:67], v[72:73], off
	global_load_dwordx4 v[68:71], v[74:75], off
	global_load_dwordx4 v[72:75], v[80:81], off
	global_load_dwordx4 v[76:79], v[82:83], off
	global_load_dwordx4 v[80:83], v[90:91], off offset:256
	global_load_dwordx4 v[84:87], v[92:93], off offset:256
	global_load_dwordx4 v[88:91], v[110:111], off offset:256
	global_load_dwordx4 v[92:95], v[112:113], off offset:256
	ds_read_b128 v[110:113], v108
	ds_read_b128 v[114:117], v109 offset:36864
	ds_read_b128 v[118:121], v108 offset:32
	ds_read_b128 v[122:125], v109 offset:36896
	ds_read_b128 v[126:129], v109 offset:41472
	ds_read_b128 v[130:133], v109 offset:41504
	s_waitcnt lgkmcnt(4)
	v_mfma_f32_32x32x16_bf16 v[48:63], v[110:113], v[114:117], v[48:63]
	s_waitcnt lgkmcnt(1)
	v_mfma_f32_32x32x16_bf16 v[32:47], v[110:113], v[126:129], v[32:47]
	ds_read_b128 v[110:113], v108 offset:4608
	ds_read_b128 v[134:137], v108 offset:4640
	s_waitcnt lgkmcnt(1)
	v_mfma_f32_32x32x16_bf16 v[16:31], v[110:113], v[114:117], v[16:31]
	v_mfma_f32_32x32x16_bf16 v[0:15], v[110:113], v[126:129], v[0:15]
	v_mfma_f32_32x32x16_bf16 v[48:63], v[118:121], v[122:125], v[48:63]
	v_mfma_f32_32x32x16_bf16 v[32:47], v[118:121], v[130:133], v[32:47]
	s_waitcnt lgkmcnt(0)
	v_mfma_f32_32x32x16_bf16 v[16:31], v[134:137], v[122:125], v[16:31]
	ds_read_b128 v[110:113], v108 offset:64
	ds_read_b128 v[114:117], v109 offset:36928
	ds_read_b128 v[118:121], v108 offset:96
	ds_read_b128 v[122:125], v109 offset:36960
	v_mfma_f32_32x32x16_bf16 v[0:15], v[134:137], v[130:133], v[0:15]
	ds_read_b128 v[126:129], v109 offset:41536
	ds_read_b128 v[130:133], v109 offset:41568
	s_waitcnt lgkmcnt(4)
	v_mfma_f32_32x32x16_bf16 v[48:63], v[110:113], v[114:117], v[48:63]
	s_waitcnt lgkmcnt(1)
	v_mfma_f32_32x32x16_bf16 v[32:47], v[110:113], v[126:129], v[32:47]
	ds_read_b128 v[110:113], v108 offset:4672
	ds_read_b128 v[134:137], v108 offset:4704
	s_waitcnt lgkmcnt(1)
	v_mfma_f32_32x32x16_bf16 v[16:31], v[110:113], v[114:117], v[16:31]
	v_mfma_f32_32x32x16_bf16 v[0:15], v[110:113], v[126:129], v[0:15]
	v_mfma_f32_32x32x16_bf16 v[48:63], v[118:121], v[122:125], v[48:63]
	v_mfma_f32_32x32x16_bf16 v[32:47], v[118:121], v[130:133], v[32:47]
	s_waitcnt lgkmcnt(0)
	v_mfma_f32_32x32x16_bf16 v[16:31], v[134:137], v[122:125], v[16:31]
	v_mfma_f32_32x32x16_bf16 v[0:15], v[134:137], v[130:133], v[0:15]
	v_add_u32_e32 v110, 18432, v96
	s_waitcnt vmcnt(15)
	ds_write_b128 v110, v[222:225]
	s_waitcnt vmcnt(14)
	ds_write_b128 v110, v[226:229] offset:4608
	s_waitcnt vmcnt(13)
	ds_write_b128 v110, v[230:233] offset:9216
	s_waitcnt vmcnt(12)
	ds_write_b128 v110, v[234:237] offset:13824
	s_waitcnt vmcnt(11)
	ds_write_b128 v110, v[238:241] offset:36864
	s_waitcnt vmcnt(10)
	ds_write_b128 v110, v[242:245] offset:41472
	s_waitcnt vmcnt(9)
	ds_write_b128 v110, v[248:251] offset:46080
	s_waitcnt vmcnt(8)
	ds_write_b128 v110, v[252:255] offset:50688
	s_waitcnt lgkmcnt(0)
	s_barrier
	v_lshl_add_u64 v[248:249], v[106:107], 0, s[16:17]
	v_add_co_u32_e32 v250, vcc, 0xea1d000, v248
	s_nop 1
	v_addc_co_u32_e32 v251, vcc, 0, v249, vcc
	v_add_co_u32_e32 v252, vcc, 0xea2d000, v248
	s_nop 1
	v_addc_co_u32_e32 v253, vcc, 0, v249, vcc
	v_add_co_u32_e32 v110, vcc, 0xea3d000, v248
	s_nop 1
	v_addc_co_u32_e32 v111, vcc, 0, v249, vcc
	v_add_co_u32_e32 v112, vcc, 0xea4d000, v248
	s_nop 1
	v_addc_co_u32_e32 v113, vcc, 0, v249, vcc
	v_lshl_add_u64 v[230:231], v[98:99], 0, s[38:39]
	v_lshl_add_u64 v[232:233], v[100:101], 0, s[38:39]
	v_lshl_add_u64 v[238:239], v[102:103], 0, s[38:39]
	v_lshl_add_u64 v[240:241], v[104:105], 0, s[38:39]
	global_load_dwordx4 v[222:225], v[230:231], off offset:128
	global_load_dwordx4 v[226:229], v[232:233], off offset:128
	global_load_dwordx4 v[230:233], v[238:239], off offset:128
	global_load_dwordx4 v[234:237], v[240:241], off offset:128
	global_load_dwordx4 v[238:241], v[250:251], off offset:384
	global_load_dwordx4 v[242:245], v[252:253], off offset:384
	global_load_dwordx4 v[248:251], v[110:111], off offset:384
	global_load_dwordx4 v[252:255], v[112:113], off offset:384
	ds_read_b128 v[110:113], v108 offset:18432
	ds_read_b128 v[114:117], v109 offset:55296
	ds_read_b128 v[118:121], v108 offset:18464
	ds_read_b128 v[122:125], v109 offset:55328
	ds_read_b128 v[126:129], v109 offset:59904
	ds_read_b128 v[130:133], v109 offset:59936
	s_waitcnt lgkmcnt(4)
	v_mfma_f32_32x32x16_bf16 v[48:63], v[110:113], v[114:117], v[48:63]
	s_waitcnt lgkmcnt(1)
	v_mfma_f32_32x32x16_bf16 v[32:47], v[110:113], v[126:129], v[32:47]
	ds_read_b128 v[110:113], v108 offset:23040
	ds_read_b128 v[134:137], v108 offset:23072
	s_waitcnt lgkmcnt(1)
	v_mfma_f32_32x32x16_bf16 v[16:31], v[110:113], v[114:117], v[16:31]
	v_mfma_f32_32x32x16_bf16 v[0:15], v[110:113], v[126:129], v[0:15]
	v_mfma_f32_32x32x16_bf16 v[48:63], v[118:121], v[122:125], v[48:63]
	v_mfma_f32_32x32x16_bf16 v[32:47], v[118:121], v[130:133], v[32:47]
	s_waitcnt lgkmcnt(0)
; __device__ __forceinline__ f32x16 mfma32(bf16x8 a, bf16x8 b, f32x16 c) { return __builtin_amdgcn_mfma_f32_32x32x16_bf16(a, b, c, 0, 0, 0); }
; __device__ __forceinline__ void lds_barrier() { asm volatile("s_waitcnt lgkmcnt(0)\n\ts_barrier" ::: "memory"); }
; template <class ARowF, class KOffF>
; __device__ __forceinline__ void gemm_kloop(f32x16 (&acc)[2][2], ARowF arow, KOffF koff, const u16* __restrict__ Bt, int m0, int n0, unsigned char* smem) {
;     ...
;   for (int kt = 0; kt < 16; ++kt) {
;     const int buf = kt & 1;
;     if (kt + 1 < 16) {
;       const size_t ko = koff((kt + 1) * 64); const int kb = (kt + 1) * 64;
;       ra0 = *(const u32x4*)(pa0 + ko); ra1 = *(const u32x4*)(pa1 + ko); ra2 = *(const u32x4*)(pa2 + ko); ra3 = *(const u32x4*)(pa3 + ko);
;       rb0 = *(const u32x4*)(pb0 + kb); rb1 = *(const u32x4*)(pb0 + 32 * 1024 + kb); rb2 = *(const u32x4*)(pb0 + 64 * 1024 + kb); rb3 = *(const u32x4*)(pb0 + 96 * 1024 + kb);
;     }
;     const u16* cA = sA + buf * 128 * 72 + (wm * 64 + l31) * 72 + hf * 8;
;     const u16* cB = sB + buf * 128 * 72 + (wn * 64 + l31) * 72 + hf * 8;
; #pragma unroll
;     for (int ks = 0; ks < 4; ++ks) {
;       bf16x8 a0 = *(const bf16x8*)(cA + ks * 16);
;       bf16x8 a1 = *(const bf16x8*)(cA + 32 * 72 + ks * 16);
;       bf16x8 b0 = *(const bf16x8*)(cB + ks * 16);
;       bf16x8 b1 = *(const bf16x8*)(cB + 32 * 72 + ks * 16);
;       acc[0][0] = mfma32(a0, b0, acc[0][0]);
;       acc[0][1] = mfma32(a0, b1, acc[0][1]);
;       acc[1][0] = mfma32(a1, b0, acc[1][0]);
;       acc[1][1] = mfma32(a1, b1, acc[1][1]);
;     }
;     if (kt + 1 < 16) {
;       u16* wA = wA0 + (buf ^ 1) * 128 * 72; u16* wB = wB0 + (buf ^ 1) * 128 * 72;
;       *(u32x4*)(wA) = ra0; *(u32x4*)(wA + 32 * 72) = ra1; *(u32x4*)(wA + 64 * 72) = ra2; *(u32x4*)(wA + 96 * 72) = ra3;
;       *(u32x4*)(wB) = rb0; *(u32x4*)(wB + 32 * 72) = rb1; *(u32x4*)(wB + 64 * 72) = rb2; *(u32x4*)(wB + 96 * 72) = rb3;
;     }
;     lds_barrier();
;   }
	v_mfma_f32_32x32x16_bf16 v[16:31], v[134:137], v[122:125], v[16:31]
	ds_read_b128 v[110:113], v108 offset:18496
	ds_read_b128 v[114:117], v109 offset:55360
	ds_read_b128 v[118:121], v108 offset:18528
	ds_read_b128 v[122:125], v109 offset:55392
	v_mfma_f32_32x32x16_bf16 v[0:15], v[134:137], v[130:133], v[0:15]
	ds_read_b128 v[126:129], v109 offset:59968
	ds_read_b128 v[130:133], v109 offset:60000
	s_waitcnt lgkmcnt(4)
	v_mfma_f32_32x32x16_bf16 v[48:63], v[110:113], v[114:117], v[48:63]
	s_waitcnt lgkmcnt(1)
	v_mfma_f32_32x32x16_bf16 v[32:47], v[110:113], v[126:129], v[32:47]
	ds_read_b128 v[110:113], v108 offset:23104
	ds_read_b128 v[134:137], v108 offset:23136
	s_waitcnt lgkmcnt(1)
	v_mfma_f32_32x32x16_bf16 v[16:31], v[110:113], v[114:117], v[16:31]
	v_mfma_f32_32x32x16_bf16 v[0:15], v[110:113], v[126:129], v[0:15]
	v_mfma_f32_32x32x16_bf16 v[48:63], v[118:121], v[122:125], v[48:63]
	v_mfma_f32_32x32x16_bf16 v[32:47], v[118:121], v[130:133], v[32:47]
	s_waitcnt lgkmcnt(0)
	v_mfma_f32_32x32x16_bf16 v[16:31], v[134:137], v[122:125], v[16:31]
	v_mfma_f32_32x32x16_bf16 v[0:15], v[134:137], v[130:133], v[0:15]
	v_mov_b32_e32 v110, v96
	s_waitcnt vmcnt(15)
	ds_write_b128 v110, v[64:67]
	s_waitcnt vmcnt(14)
	ds_write_b128 v110, v[68:71] offset:4608
	s_waitcnt vmcnt(13)
	ds_write_b128 v110, v[72:75] offset:9216
	s_waitcnt vmcnt(12)
	ds_write_b128 v110, v[76:79] offset:13824
	s_waitcnt vmcnt(11)
	ds_write_b128 v110, v[80:83] offset:36864
	s_waitcnt vmcnt(10)
	ds_write_b128 v110, v[84:87] offset:41472
	s_waitcnt vmcnt(9)
	ds_write_b128 v110, v[88:91] offset:46080
	s_waitcnt vmcnt(8)
	ds_write_b128 v110, v[92:95] offset:50688
	s_waitcnt lgkmcnt(0)
	s_barrier
	s_add_u32 s16, s16, 0x100
	s_addc_u32 s17, s17, 0
	s_add_u32 s38, s38, 0x60c000
	s_addc_u32 s39, s39, 0
	s_cmpk_lg_i32 s16, 0x700
	s_cbranch_scc1 .Lgemm_p5b_loop
	ds_read_b128 v[110:113], v108
	ds_read_b128 v[114:117], v109 offset:36864
	ds_read_b128 v[118:121], v108 offset:32
	ds_read_b128 v[122:125], v109 offset:36896
	ds_read_b128 v[126:129], v109 offset:41472
	ds_read_b128 v[130:133], v109 offset:41504
	s_waitcnt lgkmcnt(4)
	v_mfma_f32_32x32x16_bf16 v[48:63], v[110:113], v[114:117], v[48:63]
	s_waitcnt lgkmcnt(1)
	v_mfma_f32_32x32x16_bf16 v[32:47], v[110:113], v[126:129], v[32:47]
	ds_read_b128 v[110:113], v108 offset:4608
	ds_read_b128 v[134:137], v108 offset:4640
	s_waitcnt lgkmcnt(1)
	v_mfma_f32_32x32x16_bf16 v[16:31], v[110:113], v[114:117], v[16:31]
	v_mfma_f32_32x32x16_bf16 v[0:15], v[110:113], v[126:129], v[0:15]
	v_mfma_f32_32x32x16_bf16 v[48:63], v[118:121], v[122:125], v[48:63]
	v_mfma_f32_32x32x16_bf16 v[32:47], v[118:121], v[130:133], v[32:47]
	s_waitcnt lgkmcnt(0)
	v_mfma_f32_32x32x16_bf16 v[16:31], v[134:137], v[122:125], v[16:31]
	ds_read_b128 v[110:113], v108 offset:64
	ds_read_b128 v[114:117], v109 offset:36928
	ds_read_b128 v[118:121], v108 offset:96
	ds_read_b128 v[122:125], v109 offset:36960
	v_mfma_f32_32x32x16_bf16 v[0:15], v[134:137], v[130:133], v[0:15]
	ds_read_b128 v[126:129], v109 offset:41536
	ds_read_b128 v[130:133], v109 offset:41568
	s_waitcnt lgkmcnt(4)
	v_mfma_f32_32x32x16_bf16 v[48:63], v[110:113], v[114:117], v[48:63]
	s_waitcnt lgkmcnt(1)
	v_mfma_f32_32x32x16_bf16 v[32:47], v[110:113], v[126:129], v[32:47]
	ds_read_b128 v[110:113], v108 offset:4672
	ds_read_b128 v[134:137], v108 offset:4704
	s_waitcnt lgkmcnt(1)
	v_mfma_f32_32x32x16_bf16 v[16:31], v[110:113], v[114:117], v[16:31]
	v_mfma_f32_32x32x16_bf16 v[0:15], v[110:113], v[126:129], v[0:15]
	v_mfma_f32_32x32x16_bf16 v[48:63], v[118:121], v[122:125], v[48:63]
	v_mfma_f32_32x32x16_bf16 v[32:47], v[118:121], v[130:133], v[32:47]
	s_waitcnt lgkmcnt(0)
	v_mfma_f32_32x32x16_bf16 v[16:31], v[134:137], v[122:125], v[16:31]
	v_mfma_f32_32x32x16_bf16 v[0:15], v[134:137], v[130:133], v[0:15]
	v_add_u32_e32 v110, 18432, v96
	s_waitcnt vmcnt(7)
	ds_write_b128 v110, v[222:225]
	s_waitcnt vmcnt(6)
	ds_write_b128 v110, v[226:229] offset:4608
	s_waitcnt vmcnt(5)
	ds_write_b128 v110, v[230:233] offset:9216
	s_waitcnt vmcnt(4)
	ds_write_b128 v110, v[234:237] offset:13824
	s_waitcnt vmcnt(3)
	ds_write_b128 v110, v[238:241] offset:36864
	s_waitcnt vmcnt(2)
	ds_write_b128 v110, v[242:245] offset:41472
	s_waitcnt vmcnt(1)
	ds_write_b128 v110, v[248:251] offset:46080
	s_waitcnt vmcnt(0)
	ds_write_b128 v110, v[252:255] offset:50688
	s_waitcnt lgkmcnt(0)
	s_barrier
	ds_read_b128 v[110:113], v108 offset:18432
	ds_read_b128 v[114:117], v109 offset:55296
	ds_read_b128 v[118:121], v108 offset:18464
	ds_read_b128 v[122:125], v109 offset:55328
	ds_read_b128 v[126:129], v109 offset:59904
	ds_read_b128 v[130:133], v109 offset:59936
	s_waitcnt lgkmcnt(4)
	v_mfma_f32_32x32x16_bf16 v[48:63], v[110:113], v[114:117], v[48:63]
	s_waitcnt lgkmcnt(1)
	v_mfma_f32_32x32x16_bf16 v[32:47], v[110:113], v[126:129], v[32:47]
	ds_read_b128 v[110:113], v108 offset:23040
	ds_read_b128 v[134:137], v108 offset:23072
	s_waitcnt lgkmcnt(1)
	v_mfma_f32_32x32x16_bf16 v[16:31], v[110:113], v[114:117], v[16:31]
	v_mfma_f32_32x32x16_bf16 v[0:15], v[110:113], v[126:129], v[0:15]
	v_mfma_f32_32x32x16_bf16 v[48:63], v[118:121], v[122:125], v[48:63]
	v_mfma_f32_32x32x16_bf16 v[32:47], v[118:121], v[130:133], v[32:47]
	s_waitcnt lgkmcnt(0)
	v_mfma_f32_32x32x16_bf16 v[16:31], v[134:137], v[122:125], v[16:31]
	ds_read_b128 v[110:113], v108 offset:18496
	ds_read_b128 v[114:117], v109 offset:55360
	ds_read_b128 v[118:121], v108 offset:18528
	ds_read_b128 v[122:125], v109 offset:55392
	v_mfma_f32_32x32x16_bf16 v[0:15], v[134:137], v[130:133], v[0:15]
	ds_read_b128 v[126:129], v109 offset:59968
	ds_read_b128 v[130:133], v109 offset:60000
	s_waitcnt lgkmcnt(4)
	v_mfma_f32_32x32x16_bf16 v[48:63], v[110:113], v[114:117], v[48:63]
	s_waitcnt lgkmcnt(1)
	v_mfma_f32_32x32x16_bf16 v[32:47], v[110:113], v[126:129], v[32:47]
	ds_read_b128 v[110:113], v108 offset:23104
	ds_read_b128 v[134:137], v108 offset:23136
	s_waitcnt lgkmcnt(1)
	v_mfma_f32_32x32x16_bf16 v[16:31], v[110:113], v[114:117], v[16:31]
	v_mfma_f32_32x32x16_bf16 v[0:15], v[110:113], v[126:129], v[0:15]
	v_mfma_f32_32x32x16_bf16 v[48:63], v[118:121], v[122:125], v[48:63]
	v_mfma_f32_32x32x16_bf16 v[32:47], v[118:121], v[130:133], v[32:47]
	s_waitcnt lgkmcnt(0)
	v_mfma_f32_32x32x16_bf16 v[16:31], v[134:137], v[122:125], v[16:31]
	v_mfma_f32_32x32x16_bf16 v[0:15], v[134:137], v[130:133], v[0:15]
	s_waitcnt lgkmcnt(0)
	s_barrier
	s_nop 5

; __device__ __forceinline__ void lds_barrier() { asm volatile("s_waitcnt lgkmcnt(0)\n\ts_barrier" ::: "memory"); }
; __device__ __forceinline__ bool tile_map(int i, int xcd, int MT, int NT, int& mt, int& nt) {
;   int cm = (MT - xcd + 7) >> 3;
;   int ag = i / (8 * NT);
;   if (ag * 8 >= cm) return false;
;   int gs = cm - ag * 8; if (gs > 8) gs = 8;
;   int j = i - ag * 8 * NT;
;   if (j >= gs * NT) return false;
;   int al = j % gs; nt = j / gs;
;   mt = xcd + 8 * (8 * ag + al);
;   return true;
; template <class ARowF, class KOffF>
; __device__ __forceinline__ void gemm_kloop(f32x16 (&acc)[2][2], ARowF arow, KOffF koff, const u16* __restrict__ Bt, int m0, int n0, unsigned char* smem) {
;     ...
;   const u16* pa0 = arow(m0 + lr) + lc * 8; const u16* pa1 = arow(m0 + lr + 32) + lc * 8;
;   const u16* pa2 = arow(m0 + lr + 64) + lc * 8; const u16* pa3 = arow(m0 + lr + 96) + lc * 8;
;   const u16* pb0 = Bt + (size_t)(n0 + lr) * 1024 + lc * 8;
;   u32x4 ra0, ra1, ra2, ra3, rb0, rb1, rb2, rb3;
;   {
;     const size_t ko = koff(0);
;     ra0 = *(const u32x4*)(pa0 + ko); ra1 = *(const u32x4*)(pa1 + ko); ra2 = *(const u32x4*)(pa2 + ko); ra3 = *(const u32x4*)(pa3 + ko);
;     rb0 = *(const u32x4*)(pb0); rb1 = *(const u32x4*)(pb0 + 32 * 1024); rb2 = *(const u32x4*)(pb0 + 64 * 1024); rb3 = *(const u32x4*)(pb0 + 96 * 1024);
;   }
;   u16* wA0 = sA + lr * 72 + lc * 8; u16* wB0 = sB + lr * 72 + lc * 8;
;   *(u32x4*)(wA0) = ra0; *(u32x4*)(wA0 + 32 * 72) = ra1; *(u32x4*)(wA0 + 64 * 72) = ra2; *(u32x4*)(wA0 + 96 * 72) = ra3;
;   *(u32x4*)(wB0) = rb0; *(u32x4*)(wB0 + 32 * 72) = rb1; *(u32x4*)(wB0 + 64 * 72) = rb2; *(u32x4*)(wB0 + 96 * 72) = rb3;
;   lds_barrier();
.LBB0_428:
	s_sub_i32 s20, 16, s22
	s_min_u32 s23, s20, 8
	s_lshl_b32 s20, s22, 3
	s_sub_i32 s24, s33, s20
	s_lshl_b32 s20, s23, 3
	s_cmp_ge_i32 s24, s20
	s_mov_b64 s[20:21], -1
	s_cbranch_scc1 .LBB0_427
	v_cvt_f32_u32_e32 v0, s23
	s_sub_i32 s25, 0, s23
	s_abs_i32 s21, s24
	s_ashr_i32 s20, s24, 31
	v_rcp_iflag_f32_e32 v0, v0
	v_mov_b32_e32 v15, v218
	v_mul_f32_e32 v0, 0x4f7ffffe, v0
	v_cvt_u32_f32_e32 v0, v0
	v_ashrrev_i32_e32 v26, 3, v15
	v_lshlrev_b32_e32 v2, 4, v15
	v_and_b32_e32 v96, 0x70, v2
	v_readfirstlane_b32 s38, v0
	s_mul_i32 s25, s25, s38
	s_mul_hi_u32 s25, s38, s25
	s_add_i32 s38, s38, s25
	s_mul_hi_u32 s25, s21, s38
	s_mul_i32 s38, s25, s23
	s_sub_i32 s21, s21, s38
	s_add_i32 s39, s25, 1
	s_sub_i32 s38, s21, s23
	s_cmp_ge_u32 s21, s23
	s_cselect_b32 s25, s39, s25
	s_cselect_b32 s21, s38, s21
	s_add_i32 s38, s25, 1
	s_cmp_ge_u32 s21, s23
	s_cselect_b32 s21, s38, s25
	s_xor_b32 s21, s21, s20
	s_sub_i32 s20, s21, s20
	s_lshl_b32 s21, s20, 7
	s_mul_i32 s23, s20, s23
	v_add_u32_e32 v8, s21, v26
	s_sub_i32 s23, s24, s23
	v_ashrrev_i32_e32 v9, 31, v8
	s_add_i32 s23, s23, s22
	v_lshlrev_b64 v[24:25], 11, v[8:9]
	s_lshl_b32 s22, s23, 10
	v_lshl_add_u64 v[8:9], s[6:7], 0, v[24:25]
	s_or_b32 s38, s22, s27
	v_lshl_add_u64 v[8:9], v[8:9], 0, v[96:97]
	v_add_u32_e32 v0, s38, v26
	v_add_co_u32_e32 v10, vcc, s28, v8
	v_ashrrev_i32_e32 v1, 31, v0
	s_nop 0
	v_addc_co_u32_e32 v11, vcc, 0, v9, vcc
	v_lshlrev_b64 v[16:17], 11, v[0:1]
	global_load_dwordx4 v[72:75], v[8:9], off
	global_load_dwordx4 v[84:87], v[10:11], off
	v_add_co_u32_e32 v10, vcc, s29, v8
	v_lshl_add_u64 v[18:19], v[16:17], 0, s[14:15]
	v_lshl_add_u64 v[20:21], v[16:17], 0, s[16:17]
	v_lshl_add_u64 v[22:23], v[16:17], 0, s[18:19]
	v_addc_co_u32_e32 v11, vcc, 0, v9, vcc
	v_lshl_add_u64 v[0:1], s[4:5], 0, v[16:17]
	v_lshl_add_u64 v[2:3], s[4:5], 0, v[18:19]
	v_lshl_add_u64 v[4:5], s[4:5], 0, v[20:21]
	v_lshl_add_u64 v[6:7], s[4:5], 0, v[22:23]
	v_add_co_u32_e32 v8, vcc, s30, v8
	v_lshl_add_u64 v[0:1], v[0:1], 0, v[96:97]
	v_lshl_add_u64 v[2:3], v[2:3], 0, v[96:97]
	v_lshl_add_u64 v[4:5], v[4:5], 0, v[96:97]
	v_lshl_add_u64 v[6:7], v[6:7], 0, v[96:97]
	v_addc_co_u32_e32 v9, vcc, 0, v9, vcc
	global_load_dwordx4 v[88:91], v[10:11], off
	global_load_dwordx4 v[92:95], v[8:9], off
	global_load_dwordx4 v[64:67], v[0:1], off
	global_load_dwordx4 v[68:71], v[2:3], off
	global_load_dwordx4 v[76:79], v[4:5], off
	global_load_dwordx4 v[80:83], v[6:7], off
	v_mul_lo_u32 v26, v26, s31
	v_add3_u32 v108, 16, v26, v96
	v_and_b32_e32 v27, 31, v15
	v_lshrrev_b32_e32 v28, 1, v15
	v_and_b32_e32 v15, 0x5f, v15
	v_and_or_b32 v27, v28, s34, v27
	v_mov_b32_e32 v0, 0
	v_and_b32_e32 v28, 16, v28
	v_mul_u32_u24_e32 v15, 0x90, v15
	v_mul_lo_u32 v26, v27, s31
	v_or_b32_e32 v24, v24, v96
	v_or_b32_e32 v16, v16, v96
	v_or_b32_e32 v18, v18, v96
	v_or_b32_e32 v20, v20, v96
	v_or_b32_e32 v22, v22, v96
	s_mov_b32 s39, 0
	s_mov_b64 s[22:23], 0
	v_mov_b32_e32 v1, v0
	v_mov_b32_e32 v2, v0
	v_mov_b32_e32 v3, v0
	v_mov_b32_e32 v4, v0
	v_mov_b32_e32 v5, v0
	v_mov_b32_e32 v6, v0
	v_mov_b32_e32 v7, v0
	v_mov_b32_e32 v8, v0
	v_mov_b32_e32 v9, v0
	v_mov_b32_e32 v10, v0
	v_mov_b32_e32 v11, v0
	v_mov_b32_e32 v12, v0
	v_mov_b32_e32 v13, v0
	v_mov_b32_e32 v14, v0
	v_add3_u32 v109, 16, v15, v28
	v_add3_u32 v110, 16, v26, v28
	v_lshl_add_u64 v[98:99], s[36:37], 0, v[24:25]
	v_lshl_add_u64 v[100:101], s[12:13], 0, v[16:17]
	v_lshl_add_u64 v[102:103], s[12:13], 0, v[18:19]
	v_lshl_add_u64 v[104:105], s[12:13], 0, v[20:21]
	v_lshl_add_u64 v[106:107], s[12:13], 0, v[22:23]
	v_mov_b32_e32 v15, v0
	v_mov_b32_e32 v16, v0
	v_mov_b32_e32 v17, v0
	v_mov_b32_e32 v18, v0
	v_mov_b32_e32 v19, v0
	v_mov_b32_e32 v20, v0
	v_mov_b32_e32 v21, v0
	v_mov_b32_e32 v22, v0
	v_mov_b32_e32 v23, v0
	v_mov_b32_e32 v24, v0
	v_mov_b32_e32 v25, v0
	v_mov_b32_e32 v26, v0
	v_lshl_add_u64 v[248:249], v[98:99], 0, s[22:23]
	v_add_co_u32_e32 v250, vcc, 0xec1d000, v248
	v_lshl_add_u64 v[238:239], v[100:101], 0, s[22:23]
	s_nop 0
	v_addc_co_u32_e32 v251, vcc, 0, v249, vcc
	v_add_co_u32_e32 v252, vcc, 0xec2d000, v248
	v_lshl_add_u64 v[240:241], v[102:103], 0, s[22:23]
	s_nop 0
	v_addc_co_u32_e32 v253, vcc, 0, v249, vcc
	v_add_co_u32_e32 v112, vcc, 0xec3d000, v248
	global_load_dwordx4 v[222:225], v[238:239], off
	global_load_dwordx4 v[226:229], v[240:241], off
	v_addc_co_u32_e32 v113, vcc, 0, v249, vcc
	v_lshl_add_u64 v[238:239], v[104:105], 0, s[22:23]
	v_lshl_add_u64 v[240:241], v[106:107], 0, s[22:23]
	v_add_co_u32_e32 v114, vcc, 0xec4d000, v248
	global_load_dwordx4 v[230:233], v[238:239], off
	global_load_dwordx4 v[234:237], v[240:241], off
	s_nop 0
	global_load_dwordx4 v[238:241], v[250:251], off offset:128
	global_load_dwordx4 v[242:245], v[252:253], off offset:128
	v_addc_co_u32_e32 v115, vcc, 0, v249, vcc
	global_load_dwordx4 v[248:251], v[112:113], off offset:128
	global_load_dwordx4 v[252:255], v[114:115], off offset:128
	s_waitcnt vmcnt(15)
	ds_write_b128 v108, v[72:75] offset:36864
	s_waitcnt vmcnt(14)
	ds_write_b128 v108, v[84:87] offset:41472
	s_waitcnt vmcnt(13)
	ds_write_b128 v108, v[88:91] offset:46080
	s_waitcnt vmcnt(12)
	ds_write_b128 v108, v[92:95] offset:50688
	s_waitcnt vmcnt(11)
	ds_write_b128 v108, v[64:67]
	s_waitcnt vmcnt(10)
	ds_write_b128 v108, v[68:71] offset:4608
	s_waitcnt vmcnt(9)
	ds_write_b128 v108, v[76:79] offset:9216
	s_waitcnt vmcnt(8)
	ds_write_b128 v108, v[80:83] offset:13824
	s_waitcnt lgkmcnt(0)
	s_barrier
	v_mov_b32_e32 v27, v0
	v_mov_b32_e32 v28, v0
	v_mov_b32_e32 v29, v0
	v_mov_b32_e32 v30, v0
	v_mov_b32_e32 v31, v0
	v_mov_b32_e32 v32, v0
	v_mov_b32_e32 v33, v0
	v_mov_b32_e32 v34, v0
	v_mov_b32_e32 v35, v0
	v_mov_b32_e32 v36, v0
	v_mov_b32_e32 v37, v0
	v_mov_b32_e32 v38, v0
	v_mov_b32_e32 v39, v0
	v_mov_b32_e32 v40, v0
	v_mov_b32_e32 v41, v0
	v_mov_b32_e32 v42, v0
	v_mov_b32_e32 v43, v0
	v_mov_b32_e32 v44, v0
	v_mov_b32_e32 v45, v0
	v_mov_b32_e32 v46, v0
	v_mov_b32_e32 v47, v0
	v_mov_b32_e32 v48, v0
	v_mov_b32_e32 v49, v0
	v_mov_b32_e32 v50, v0
	v_mov_b32_e32 v51, v0
	v_mov_b32_e32 v52, v0
	v_mov_b32_e32 v53, v0
	v_mov_b32_e32 v54, v0
	v_mov_b32_e32 v55, v0
	v_mov_b32_e32 v56, v0
	v_mov_b32_e32 v57, v0
	v_mov_b32_e32 v58, v0
	v_mov_b32_e32 v59, v0
	v_mov_b32_e32 v60, v0
	v_mov_b32_e32 v61, v0
	v_mov_b32_e32 v62, v0
	v_mov_b32_e32 v63, v0
	s_branch .LBB0_431
; __device__ __forceinline__ f32x16 mfma32(bf16x8 a, bf16x8 b, f32x16 c) { return __builtin_amdgcn_mfma_f32_32x32x16_bf16(a, b, c, 0, 0, 0); }
; template <class ARowF, class KOffF>
; __device__ __forceinline__ void gemm_kloop(f32x16 (&acc)[2][2], ARowF arow, KOffF koff, const u16* __restrict__ Bt, int m0, int n0, unsigned char* smem) {
;     ...
;   for (int kt = 0; kt < 16; ++kt) {
;     const int buf = kt & 1;
;     if (kt + 1 < 16) {
;       const size_t ko = koff((kt + 1) * 64); const int kb = (kt + 1) * 64;
;       ra0 = *(const u32x4*)(pa0 + ko); ra1 = *(const u32x4*)(pa1 + ko); ra2 = *(const u32x4*)(pa2 + ko); ra3 = *(const u32x4*)(pa3 + ko);
;       rb0 = *(const u32x4*)(pb0 + kb); rb1 = *(const u32x4*)(pb0 + 32 * 1024 + kb); rb2 = *(const u32x4*)(pb0 + 64 * 1024 + kb); rb3 = *(const u32x4*)(pb0 + 96 * 1024 + kb);
;     }
;     const u16* cA = sA + buf * 128 * 72 + (wm * 64 + l31) * 72 + hf * 8;
;     const u16* cB = sB + buf * 128 * 72 + (wn * 64 + l31) * 72 + hf * 8;
; #pragma unroll
;     for (int ks = 0; ks < 4; ++ks) {
;       bf16x8 a0 = *(const bf16x8*)(cA + ks * 16);
;       bf16x8 a1 = *(const bf16x8*)(cA + 32 * 72 + ks * 16);
;       bf16x8 b0 = *(const bf16x8*)(cB + ks * 16);
;       bf16x8 b1 = *(const bf16x8*)(cB + 32 * 72 + ks * 16);
;       acc[0][0] = mfma32(a0, b0, acc[0][0]);
;       acc[0][1] = mfma32(a0, b1, acc[0][1]);
;       acc[1][0] = mfma32(a1, b0, acc[1][0]);
;       acc[1][1] = mfma32(a1, b1, acc[1][1]);
.LBB0_431:
.Lgemm_p6_loop:
	v_lshl_add_u64 v[88:89], v[98:99], 0, s[22:23]
	v_add_co_u32_e32 v90, vcc, 0xec1d000, v88
	v_lshl_add_u64 v[72:73], v[100:101], 0, s[22:23]
	s_nop 0
	v_addc_co_u32_e32 v91, vcc, 0, v89, vcc
	v_add_co_u32_e32 v92, vcc, 0xec2d000, v88
	v_lshl_add_u64 v[74:75], v[102:103], 0, s[22:23]
	s_nop 0
	v_addc_co_u32_e32 v93, vcc, 0, v89, vcc
	v_add_co_u32_e32 v112, vcc, 0xec3d000, v88
	global_load_dwordx4 v[64:67], v[72:73], off offset:128
	global_load_dwordx4 v[68:71], v[74:75], off offset:128
	v_addc_co_u32_e32 v113, vcc, 0, v89, vcc
	v_lshl_add_u64 v[72:73], v[104:105], 0, s[22:23]
	v_lshl_add_u64 v[74:75], v[106:107], 0, s[22:23]
	v_add_co_u32_e32 v114, vcc, 0xec4d000, v88
	global_load_dwordx4 v[76:79], v[72:73], off offset:128
	global_load_dwordx4 v[80:83], v[74:75], off offset:128
	s_nop 0
	global_load_dwordx4 v[72:75], v[90:91], off offset:256
	global_load_dwordx4 v[84:87], v[92:93], off offset:256
	v_addc_co_u32_e32 v115, vcc, 0, v89, vcc
	global_load_dwordx4 v[88:91], v[112:113], off offset:256
	global_load_dwordx4 v[92:95], v[114:115], off offset:256
	ds_read_b128 v[112:115], v110
	ds_read_b128 v[116:119], v109 offset:36864
	ds_read_b128 v[120:123], v110 offset:32
	ds_read_b128 v[124:127], v109 offset:36896
	ds_read_b128 v[128:131], v109 offset:41472
	ds_read_b128 v[132:135], v109 offset:41504
	s_waitcnt lgkmcnt(0)
	v_mfma_f32_32x32x16_bf16 v[48:63], v[112:115], v[116:119], v[48:63]
	v_mfma_f32_32x32x16_bf16 v[32:47], v[112:115], v[128:131], v[32:47]
	ds_read_b128 v[112:115], v110 offset:4608
	ds_read_b128 v[136:139], v110 offset:4640
	s_waitcnt lgkmcnt(1)
	v_mfma_f32_32x32x16_bf16 v[16:31], v[112:115], v[116:119], v[16:31]
	v_mfma_f32_32x32x16_bf16 v[0:15], v[112:115], v[128:131], v[0:15]
	v_mfma_f32_32x32x16_bf16 v[48:63], v[120:123], v[124:127], v[48:63]
	v_mfma_f32_32x32x16_bf16 v[32:47], v[120:123], v[132:135], v[32:47]
	s_waitcnt lgkmcnt(0)
	v_mfma_f32_32x32x16_bf16 v[16:31], v[136:139], v[124:127], v[16:31]
	ds_read_b128 v[112:115], v110 offset:64
	ds_read_b128 v[116:119], v109 offset:36928
	ds_read_b128 v[120:123], v110 offset:96
	ds_read_b128 v[124:127], v109 offset:36960
	v_mfma_f32_32x32x16_bf16 v[0:15], v[136:139], v[132:135], v[0:15]
	ds_read_b128 v[128:131], v109 offset:41536
	ds_read_b128 v[132:135], v109 offset:41568
	s_waitcnt lgkmcnt(4)
	v_mfma_f32_32x32x16_bf16 v[48:63], v[112:115], v[116:119], v[48:63]
	s_waitcnt lgkmcnt(1)
	v_mfma_f32_32x32x16_bf16 v[32:47], v[112:115], v[128:131], v[32:47]
	ds_read_b128 v[112:115], v110 offset:4672
	ds_read_b128 v[136:139], v110 offset:4704
	s_waitcnt lgkmcnt(1)
	v_mfma_f32_32x32x16_bf16 v[16:31], v[112:115], v[116:119], v[16:31]
	v_mfma_f32_32x32x16_bf16 v[0:15], v[112:115], v[128:131], v[0:15]
	v_mfma_f32_32x32x16_bf16 v[48:63], v[120:123], v[124:127], v[48:63]
	v_mfma_f32_32x32x16_bf16 v[32:47], v[120:123], v[132:135], v[32:47]
	s_waitcnt lgkmcnt(0)
	v_mfma_f32_32x32x16_bf16 v[16:31], v[136:139], v[124:127], v[16:31]
	v_mfma_f32_32x32x16_bf16 v[0:15], v[136:139], v[132:135], v[0:15]
	v_add_u32_e32 v96, 18432, v108
	s_waitcnt vmcnt(15)
	ds_write_b128 v96, v[222:225]
	s_waitcnt vmcnt(14)
	ds_write_b128 v96, v[226:229] offset:4608
	s_waitcnt vmcnt(13)
	ds_write_b128 v96, v[230:233] offset:9216
	s_waitcnt vmcnt(12)
	ds_write_b128 v96, v[234:237] offset:13824
	s_waitcnt vmcnt(11)
	ds_write_b128 v96, v[238:241] offset:36864
	s_waitcnt vmcnt(10)
	ds_write_b128 v96, v[242:245] offset:41472
	s_waitcnt vmcnt(9)
	ds_write_b128 v96, v[248:251] offset:46080
	s_waitcnt vmcnt(8)
	ds_write_b128 v96, v[252:255] offset:50688
	s_waitcnt lgkmcnt(0)
	s_barrier
	v_lshl_add_u64 v[248:249], v[98:99], 0, s[22:23]
	v_add_co_u32_e32 v250, vcc, 0xec1d000, v248
	v_lshl_add_u64 v[238:239], v[100:101], 0, s[22:23]
	s_nop 0
	v_addc_co_u32_e32 v251, vcc, 0, v249, vcc
	v_add_co_u32_e32 v252, vcc, 0xec2d000, v248
	v_lshl_add_u64 v[240:241], v[102:103], 0, s[22:23]
	s_nop 0
	v_addc_co_u32_e32 v253, vcc, 0, v249, vcc
	v_add_co_u32_e32 v112, vcc, 0xec3d000, v248
	global_load_dwordx4 v[222:225], v[238:239], off offset:256
	global_load_dwordx4 v[226:229], v[240:241], off offset:256
	v_addc_co_u32_e32 v113, vcc, 0, v249, vcc
	v_lshl_add_u64 v[238:239], v[104:105], 0, s[22:23]
	v_lshl_add_u64 v[240:241], v[106:107], 0, s[22:23]
	v_add_co_u32_e32 v114, vcc, 0xec4d000, v248
	global_load_dwordx4 v[230:233], v[238:239], off offset:256
	global_load_dwordx4 v[234:237], v[240:241], off offset:256
	s_nop 0
	global_load_dwordx4 v[238:241], v[250:251], off offset:384
	global_load_dwordx4 v[242:245], v[252:253], off offset:384
	v_addc_co_u32_e32 v115, vcc, 0, v249, vcc
	global_load_dwordx4 v[248:251], v[112:113], off offset:384
	global_load_dwordx4 v[252:255], v[114:115], off offset:384
	ds_read_b128 v[112:115], v110 offset:18432
	ds_read_b128 v[116:119], v109 offset:55296
	ds_read_b128 v[120:123], v110 offset:18464
	ds_read_b128 v[124:127], v109 offset:55328
	ds_read_b128 v[128:131], v109 offset:59904
	ds_read_b128 v[132:135], v109 offset:59936
	s_waitcnt lgkmcnt(0)
	v_mfma_f32_32x32x16_bf16 v[48:63], v[112:115], v[116:119], v[48:63]
	v_mfma_f32_32x32x16_bf16 v[32:47], v[112:115], v[128:131], v[32:47]
	ds_read_b128 v[112:115], v110 offset:23040
	ds_read_b128 v[136:139], v110 offset:23072
	s_waitcnt lgkmcnt(1)
	v_mfma_f32_32x32x16_bf16 v[16:31], v[112:115], v[116:119], v[16:31]
	v_mfma_f32_32x32x16_bf16 v[0:15], v[112:115], v[128:131], v[0:15]
	v_mfma_f32_32x32x16_bf16 v[48:63], v[120:123], v[124:127], v[48:63]
	v_mfma_f32_32x32x16_bf16 v[32:47], v[120:123], v[132:135], v[32:47]
	s_waitcnt lgkmcnt(0)
; __device__ __forceinline__ f32x16 mfma32(bf16x8 a, bf16x8 b, f32x16 c) { return __builtin_amdgcn_mfma_f32_32x32x16_bf16(a, b, c, 0, 0, 0); }
; __device__ __forceinline__ void lds_barrier() { asm volatile("s_waitcnt lgkmcnt(0)\n\ts_barrier" ::: "memory"); }
; template <class ARowF, class KOffF>
; __device__ __forceinline__ void gemm_kloop(f32x16 (&acc)[2][2], ARowF arow, KOffF koff, const u16* __restrict__ Bt, int m0, int n0, unsigned char* smem) {
;     ...
;   for (int kt = 0; kt < 16; ++kt) {
;     const int buf = kt & 1;
;     if (kt + 1 < 16) {
;       const size_t ko = koff((kt + 1) * 64); const int kb = (kt + 1) * 64;
;       ra0 = *(const u32x4*)(pa0 + ko); ra1 = *(const u32x4*)(pa1 + ko); ra2 = *(const u32x4*)(pa2 + ko); ra3 = *(const u32x4*)(pa3 + ko);
;       rb0 = *(const u32x4*)(pb0 + kb); rb1 = *(const u32x4*)(pb0 + 32 * 1024 + kb); rb2 = *(const u32x4*)(pb0 + 64 * 1024 + kb); rb3 = *(const u32x4*)(pb0 + 96 * 1024 + kb);
;     }
;     const u16* cA = sA + buf * 128 * 72 + (wm * 64 + l31) * 72 + hf * 8;
;     const u16* cB = sB + buf * 128 * 72 + (wn * 64 + l31) * 72 + hf * 8;
; #pragma unroll
;     for (int ks = 0; ks < 4; ++ks) {
;       bf16x8 a0 = *(const bf16x8*)(cA + ks * 16);
;       bf16x8 a1 = *(const bf16x8*)(cA + 32 * 72 + ks * 16);
;       bf16x8 b0 = *(const bf16x8*)(cB + ks * 16);
;       bf16x8 b1 = *(const bf16x8*)(cB + 32 * 72 + ks * 16);
;       acc[0][0] = mfma32(a0, b0, acc[0][0]);
;       acc[0][1] = mfma32(a0, b1, acc[0][1]);
;       acc[1][0] = mfma32(a1, b0, acc[1][0]);
;       acc[1][1] = mfma32(a1, b1, acc[1][1]);
;     }
;     if (kt + 1 < 16) {
;       u16* wA = wA0 + (buf ^ 1) * 128 * 72; u16* wB = wB0 + (buf ^ 1) * 128 * 72;
;       *(u32x4*)(wA) = ra0; *(u32x4*)(wA + 32 * 72) = ra1; *(u32x4*)(wA + 64 * 72) = ra2; *(u32x4*)(wA + 96 * 72) = ra3;
;       *(u32x4*)(wB) = rb0; *(u32x4*)(wB + 32 * 72) = rb1; *(u32x4*)(wB + 64 * 72) = rb2; *(u32x4*)(wB + 96 * 72) = rb3;
;     }
;     lds_barrier();
;   }
	v_mfma_f32_32x32x16_bf16 v[16:31], v[136:139], v[124:127], v[16:31]
	ds_read_b128 v[112:115], v110 offset:18496
	ds_read_b128 v[116:119], v109 offset:55360
	ds_read_b128 v[120:123], v110 offset:18528
	ds_read_b128 v[124:127], v109 offset:55392
	v_mfma_f32_32x32x16_bf16 v[0:15], v[136:139], v[132:135], v[0:15]
	ds_read_b128 v[128:131], v109 offset:59968
	ds_read_b128 v[132:135], v109 offset:60000
	s_waitcnt lgkmcnt(4)
	v_mfma_f32_32x32x16_bf16 v[48:63], v[112:115], v[116:119], v[48:63]
	s_waitcnt lgkmcnt(1)
	v_mfma_f32_32x32x16_bf16 v[32:47], v[112:115], v[128:131], v[32:47]
	ds_read_b128 v[112:115], v110 offset:23104
	ds_read_b128 v[136:139], v110 offset:23136
	s_waitcnt lgkmcnt(1)
	v_mfma_f32_32x32x16_bf16 v[16:31], v[112:115], v[116:119], v[16:31]
	v_mfma_f32_32x32x16_bf16 v[0:15], v[112:115], v[128:131], v[0:15]
	v_mfma_f32_32x32x16_bf16 v[48:63], v[120:123], v[124:127], v[48:63]
	v_mfma_f32_32x32x16_bf16 v[32:47], v[120:123], v[132:135], v[32:47]
	s_waitcnt lgkmcnt(0)
	v_mfma_f32_32x32x16_bf16 v[16:31], v[136:139], v[124:127], v[16:31]
	v_mfma_f32_32x32x16_bf16 v[0:15], v[136:139], v[132:135], v[0:15]
	v_mov_b32_e32 v96, v108
	s_waitcnt vmcnt(15)
	ds_write_b128 v96, v[64:67]
	s_waitcnt vmcnt(14)
	ds_write_b128 v96, v[68:71] offset:4608
	s_waitcnt vmcnt(13)
	ds_write_b128 v96, v[76:79] offset:9216
	s_waitcnt vmcnt(12)
	ds_write_b128 v96, v[80:83] offset:13824
	s_waitcnt vmcnt(11)
	ds_write_b128 v96, v[72:75] offset:36864
	s_waitcnt vmcnt(10)
	ds_write_b128 v96, v[84:87] offset:41472
	s_waitcnt vmcnt(9)
	ds_write_b128 v96, v[88:91] offset:46080
	s_waitcnt vmcnt(8)
	ds_write_b128 v96, v[92:95] offset:50688
	s_waitcnt lgkmcnt(0)
	s_barrier
	s_add_u32 s22, s22, 0x100
	s_addc_u32 s23, s23, 0
	s_cmpk_lg_i32 s22, 0x700
	s_cbranch_scc1 .Lgemm_p6_loop
	ds_read_b128 v[112:115], v110
	ds_read_b128 v[116:119], v109 offset:36864
	ds_read_b128 v[120:123], v110 offset:32
	ds_read_b128 v[124:127], v109 offset:36896
	ds_read_b128 v[128:131], v109 offset:41472
	ds_read_b128 v[132:135], v109 offset:41504
	s_waitcnt lgkmcnt(0)
	v_mfma_f32_32x32x16_bf16 v[48:63], v[112:115], v[116:119], v[48:63]
	v_mfma_f32_32x32x16_bf16 v[32:47], v[112:115], v[128:131], v[32:47]
	ds_read_b128 v[112:115], v110 offset:4608
	ds_read_b128 v[136:139], v110 offset:4640
	s_waitcnt lgkmcnt(1)
	v_mfma_f32_32x32x16_bf16 v[16:31], v[112:115], v[116:119], v[16:31]
	v_mfma_f32_32x32x16_bf16 v[0:15], v[112:115], v[128:131], v[0:15]
	v_mfma_f32_32x32x16_bf16 v[48:63], v[120:123], v[124:127], v[48:63]
	v_mfma_f32_32x32x16_bf16 v[32:47], v[120:123], v[132:135], v[32:47]
	s_waitcnt lgkmcnt(0)
	v_mfma_f32_32x32x16_bf16 v[16:31], v[136:139], v[124:127], v[16:31]
	ds_read_b128 v[112:115], v110 offset:64
	ds_read_b128 v[116:119], v109 offset:36928
	ds_read_b128 v[120:123], v110 offset:96
	ds_read_b128 v[124:127], v109 offset:36960
	v_mfma_f32_32x32x16_bf16 v[0:15], v[136:139], v[132:135], v[0:15]
	ds_read_b128 v[128:131], v109 offset:41536
	ds_read_b128 v[132:135], v109 offset:41568
	s_waitcnt lgkmcnt(4)
	v_mfma_f32_32x32x16_bf16 v[48:63], v[112:115], v[116:119], v[48:63]
	s_waitcnt lgkmcnt(1)
	v_mfma_f32_32x32x16_bf16 v[32:47], v[112:115], v[128:131], v[32:47]
	ds_read_b128 v[112:115], v110 offset:4672
	ds_read_b128 v[136:139], v110 offset:4704
	s_waitcnt lgkmcnt(1)
	v_mfma_f32_32x32x16_bf16 v[16:31], v[112:115], v[116:119], v[16:31]
	v_mfma_f32_32x32x16_bf16 v[0:15], v[112:115], v[128:131], v[0:15]
	v_mfma_f32_32x32x16_bf16 v[48:63], v[120:123], v[124:127], v[48:63]
	v_mfma_f32_32x32x16_bf16 v[32:47], v[120:123], v[132:135], v[32:47]
	s_waitcnt lgkmcnt(0)
	v_mfma_f32_32x32x16_bf16 v[16:31], v[136:139], v[124:127], v[16:31]
	v_mfma_f32_32x32x16_bf16 v[0:15], v[136:139], v[132:135], v[0:15]
	v_add_u32_e32 v96, 18432, v108
	s_waitcnt vmcnt(7)
	ds_write_b128 v96, v[222:225]
	s_waitcnt vmcnt(6)
	ds_write_b128 v96, v[226:229] offset:4608
	s_waitcnt vmcnt(5)
	ds_write_b128 v96, v[230:233] offset:9216
	s_waitcnt vmcnt(4)
	ds_write_b128 v96, v[234:237] offset:13824
	s_waitcnt vmcnt(3)
	ds_write_b128 v96, v[238:241] offset:36864
	s_waitcnt vmcnt(2)
	ds_write_b128 v96, v[242:245] offset:41472
	s_waitcnt vmcnt(1)
	ds_write_b128 v96, v[248:251] offset:46080
	s_waitcnt vmcnt(0)
	ds_write_b128 v96, v[252:255] offset:50688
	s_waitcnt lgkmcnt(0)
	s_barrier
	ds_read_b128 v[112:115], v110 offset:18432
	ds_read_b128 v[116:119], v109 offset:55296
	ds_read_b128 v[120:123], v110 offset:18464
	ds_read_b128 v[124:127], v109 offset:55328
	ds_read_b128 v[128:131], v109 offset:59904
	ds_read_b128 v[132:135], v109 offset:59936
	s_waitcnt lgkmcnt(0)
	v_mfma_f32_32x32x16_bf16 v[48:63], v[112:115], v[116:119], v[48:63]
	v_mfma_f32_32x32x16_bf16 v[32:47], v[112:115], v[128:131], v[32:47]
	ds_read_b128 v[112:115], v110 offset:23040
	ds_read_b128 v[136:139], v110 offset:23072
	s_waitcnt lgkmcnt(1)
	v_mfma_f32_32x32x16_bf16 v[16:31], v[112:115], v[116:119], v[16:31]
	v_mfma_f32_32x32x16_bf16 v[0:15], v[112:115], v[128:131], v[0:15]
	v_mfma_f32_32x32x16_bf16 v[48:63], v[120:123], v[124:127], v[48:63]
	v_mfma_f32_32x32x16_bf16 v[32:47], v[120:123], v[132:135], v[32:47]
	s_waitcnt lgkmcnt(0)
	v_mfma_f32_32x32x16_bf16 v[16:31], v[136:139], v[124:127], v[16:31]
	ds_read_b128 v[112:115], v110 offset:18496
	ds_read_b128 v[116:119], v109 offset:55360
	ds_read_b128 v[120:123], v110 offset:18528
	ds_read_b128 v[124:127], v109 offset:55392
	v_mfma_f32_32x32x16_bf16 v[0:15], v[136:139], v[132:135], v[0:15]
	ds_read_b128 v[128:131], v109 offset:59968
	ds_read_b128 v[132:135], v109 offset:60000
	s_waitcnt lgkmcnt(4)
	v_mfma_f32_32x32x16_bf16 v[48:63], v[112:115], v[116:119], v[48:63]
	s_waitcnt lgkmcnt(1)
	v_mfma_f32_32x32x16_bf16 v[32:47], v[112:115], v[128:131], v[32:47]
	ds_read_b128 v[112:115], v110 offset:23104
	ds_read_b128 v[136:139], v110 offset:23136
	s_waitcnt lgkmcnt(1)
	v_mfma_f32_32x32x16_bf16 v[16:31], v[112:115], v[116:119], v[16:31]
	v_mfma_f32_32x32x16_bf16 v[0:15], v[112:115], v[128:131], v[0:15]
	v_mfma_f32_32x32x16_bf16 v[48:63], v[120:123], v[124:127], v[48:63]
	v_mfma_f32_32x32x16_bf16 v[32:47], v[120:123], v[132:135], v[32:47]
	s_waitcnt lgkmcnt(0)
	v_mfma_f32_32x32x16_bf16 v[16:31], v[136:139], v[124:127], v[16:31]
	v_mfma_f32_32x32x16_bf16 v[0:15], v[136:139], v[132:135], v[0:15]
	s_waitcnt lgkmcnt(0)
	s_barrier
	s_nop 5

; __global__ void __launch_bounds__(256, 2) mega(Params p) {
;   extern __shared__ __attribute__((aligned(16))) unsigned char smem[];
	.amdhsa_kernel _Z4mega6Params
		.amdhsa_group_segment_fixed_size 16
		.amdhsa_private_segment_fixed_size 0
		.amdhsa_kernarg_size 408
		.amdhsa_user_sgpr_count 2
		.amdhsa_user_sgpr_dispatch_ptr 0
		.amdhsa_user_sgpr_queue_ptr 0
		.amdhsa_user_sgpr_kernarg_segment_ptr 1
		.amdhsa_user_sgpr_dispatch_id 0
		.amdhsa_user_sgpr_kernarg_preload_length 0
		.amdhsa_user_sgpr_kernarg_preload_offset 0
		.amdhsa_user_sgpr_private_segment_size 0
		.amdhsa_uses_dynamic_stack 0
		.amdhsa_enable_private_segment 0
		.amdhsa_system_sgpr_workgroup_id_x 1
		.amdhsa_system_sgpr_workgroup_id_y 0
		.amdhsa_system_sgpr_workgroup_id_z 0
		.amdhsa_system_sgpr_workgroup_info 0
		.amdhsa_system_vgpr_workitem_id 2
		.amdhsa_next_free_vgpr 256
		.amdhsa_next_free_sgpr 100
		.amdhsa_accum_offset 256
		.amdhsa_reserve_vcc 1
		.amdhsa_float_round_mode_32 0
		.amdhsa_float_round_mode_16_64 0
		.amdhsa_float_denorm_mode_32 3
		.amdhsa_float_denorm_mode_16_64 3
		.amdhsa_dx10_clamp 1
		.amdhsa_ieee_mode 1
		.amdhsa_fp16_overflow 0
		.amdhsa_tg_split 0
		.amdhsa_exception_fp_ieee_invalid_op 0
		.amdhsa_exception_fp_denorm_src 0
		.amdhsa_exception_fp_ieee_div_zero 0
		.amdhsa_exception_fp_ieee_overflow 0
		.amdhsa_exception_fp_ieee_underflow 0
		.amdhsa_exception_fp_ieee_inexact 0
		.amdhsa_exception_int_div_zero 0
	.end_amdhsa_kernel

; __global__ void __launch_bounds__(256, 2) mega(Params p) {
;   extern __shared__ __attribute__((aligned(16))) unsigned char smem[];
amdhsa.kernels:
  - .agpr_count:     0
    .args:
      - .offset:         0
        .size:           152
        .value_kind:     by_value
      - .offset:         152
        .size:           4
        .value_kind:     hidden_block_count_x
      - .offset:         156
        .size:           4
        .value_kind:     hidden_block_count_y
      - .offset:         160
        .size:           4
        .value_kind:     hidden_block_count_z
      - .offset:         164
        .size:           2
        .value_kind:     hidden_group_size_x
      - .offset:         166
        .size:           2
        .value_kind:     hidden_group_size_y
      - .offset:         168
        .size:           2
        .value_kind:     hidden_group_size_z
      - .offset:         170
        .size:           2
        .value_kind:     hidden_remainder_x
      - .offset:         172
        .size:           2
        .value_kind:     hidden_remainder_y
      - .offset:         174
        .size:           2
        .value_kind:     hidden_remainder_z
      - .offset:         192
        .size:           8
        .value_kind:     hidden_global_offset_x
      - .offset:         200
        .size:           8
        .value_kind:     hidden_global_offset_y
      - .offset:         208
        .size:           8
        .value_kind:     hidden_global_offset_z
      - .offset:         216
        .size:           2
        .value_kind:     hidden_grid_dims
      - .offset:         240
        .size:           8
        .value_kind:     hidden_multigrid_sync_arg
      - .offset:         272
        .size:           4
        .value_kind:     hidden_dynamic_lds_size
    .group_segment_fixed_size: 16
    .kernarg_segment_align: 8
    .kernarg_segment_size: 408
    .language:       OpenCL C
    .language_version:
      - 2
      - 0
    .max_flat_workgroup_size: 256
    .name:           _Z4mega6Params
    .private_segment_fixed_size: 0
    .sgpr_count:     106
    .sgpr_spill_count: 87
    .symbol:         _Z4mega6Params.kd
    .uniform_work_group_size: 1
    .uses_dynamic_stack: false
    .vgpr_count:     256
    .vgpr_spill_count: 0
    .wavefront_size: 64
